# P2(c) LayerNorm pass rewritten with packed f32 ops (v_pk_add/mul/fma) to cut its VALU count by about a third; rest identical to the P2b-ring version
# speedup vs baseline: 1.0035x; 1.0035x over previous
.LBB0_345:
	s_and_b32 s6, s25, 3
	s_lshl_b32 s29, s6, 8
	v_or_b32_e32 v0, s29, v105
	v_lshlrev_b32_e32 v12, 2, v0
	s_waitcnt lgkmcnt(0)
	global_load_dwordx4 v[0:3], v12, s[44:45]
	global_load_dwordx4 v[4:7], v12, s[44:45] offset:16
	global_load_dwordx4 v[8:11], v12, s[46:47]
	s_nop 0
	global_load_dwordx4 v[12:15], v12, s[46:47] offset:16
	s_ashr_i32 s54, s25, 2
	s_and_b32 s4, s25, 1
	s_lshl_b32 s8, s54, 7
	s_cmp_lt_u32 s6, 2
	s_cselect_b64 s[6:7], -1, 0
	s_add_i32 s8, s3, s8
	v_cmp_eq_u32_e64 s[4:5], s4, v104
	v_mad_i64_i32 v[36:37], s[8:9], s8, v108, v[34:35]
	s_mov_b32 s49, -4
	v_mov_b32_e32 v109, v107
	s_cmpk_lg_i32 s26, 0x100
	s_cbranch_scc1 .LBB0_347
	s_movk_i32 s10, 0x4800
	s_mov_b32 s11, 0
	v_and_b32_e32 v240, 63, v164
	v_lshlrev_b32_e32 v228, 2, v240
	v_mov_b32_e32 v230, v36
	v_mov_b32_e32 v231, v37
	global_load_dwordx4 v[16:19], v[230:231], off
	global_load_dwordx4 v[20:23], v[230:231], off offset:1024
	v_lshl_add_u64 v[230:231], v[230:231], 0, s[10:11]
	global_load_dwordx4 v[24:27], v[230:231], off
	global_load_dwordx4 v[28:31], v[230:231], off offset:1024
	v_lshl_add_u64 v[230:231], v[230:231], 0, s[10:11]
	global_load_dwordx4 v[36:39], v[230:231], off
	global_load_dwordx4 v[40:43], v[230:231], off offset:1024
	v_lshl_add_u64 v[230:231], v[230:231], 0, s[10:11]
	global_load_dwordx4 v[44:47], v[230:231], off
	global_load_dwordx4 v[48:51], v[230:231], off offset:1024
	v_lshl_add_u64 v[230:231], v[230:231], 0, s[10:11]
	global_load_dwordx4 v[52:55], v[230:231], off
	global_load_dwordx4 v[56:59], v[230:231], off offset:1024
	v_lshl_add_u64 v[230:231], v[230:231], 0, s[10:11]
	global_load_dwordx4 v[60:63], v[230:231], off
	global_load_dwordx4 v[64:67], v[230:231], off offset:1024
	v_lshl_add_u64 v[230:231], v[230:231], 0, s[10:11]
	global_load_dwordx4 v[68:71], v[230:231], off
	global_load_dwordx4 v[72:75], v[230:231], off offset:1024
	v_lshl_add_u64 v[230:231], v[230:231], 0, s[10:11]
	global_load_dwordx4 v[76:79], v[230:231], off
	global_load_dwordx4 v[80:83], v[230:231], off offset:1024
	v_lshl_add_u64 v[230:231], v[230:231], 0, s[10:11]
	global_load_dwordx4 v[84:87], v[230:231], off
	global_load_dwordx4 v[88:91], v[230:231], off offset:1024
	v_lshl_add_u64 v[230:231], v[230:231], 0, s[10:11]
	global_load_dwordx4 v[92:95], v[230:231], off
	global_load_dwordx4 v[110:113], v[230:231], off offset:1024
	v_lshl_add_u64 v[230:231], v[230:231], 0, s[10:11]
	global_load_dwordx4 v[114:117], v[230:231], off
	global_load_dwordx4 v[118:121], v[230:231], off offset:1024
	v_lshl_add_u64 v[230:231], v[230:231], 0, s[10:11]
	global_load_dwordx4 v[122:125], v[230:231], off
	global_load_dwordx4 v[148:151], v[230:231], off offset:1024
	v_lshl_add_u64 v[230:231], v[230:231], 0, s[10:11]
	global_load_dwordx4 v[152:155], v[230:231], off
	global_load_dwordx4 v[156:159], v[230:231], off offset:1024
	v_lshl_add_u64 v[230:231], v[230:231], 0, s[10:11]
	global_load_dwordx4 v[160:163], v[230:231], off
	global_load_dwordx4 v[166:169], v[230:231], off offset:1024
	v_lshl_add_u64 v[230:231], v[230:231], 0, s[10:11]
	global_load_dwordx4 v[170:173], v[230:231], off
	global_load_dwordx4 v[174:177], v[230:231], off offset:1024
	v_lshl_add_u64 v[230:231], v[230:231], 0, s[10:11]
	global_load_dwordx4 v[178:181], v[230:231], off
	global_load_dwordx4 v[182:185], v[230:231], off offset:1024
	s_waitcnt vmcnt(16)
	v_mov_b32_e32 v186, 0
	v_mov_b32_e32 v187, 0
	v_lshlrev_b32_e32 v218, 16, v16
	v_and_b32_e32 v219, 0xffff0000, v16
	v_lshlrev_b32_e32 v220, 16, v20
	v_and_b32_e32 v221, 0xffff0000, v20
	v_pk_add_f32 v[218:219], v[218:219], v[220:221]
	v_pk_add_f32 v[186:187], v[186:187], v[218:219]
	v_lshlrev_b32_e32 v218, 16, v17
	v_and_b32_e32 v219, 0xffff0000, v17
	v_lshlrev_b32_e32 v220, 16, v21
	v_and_b32_e32 v221, 0xffff0000, v21
	v_pk_add_f32 v[218:219], v[218:219], v[220:221]
	v_pk_add_f32 v[186:187], v[186:187], v[218:219]
	v_lshlrev_b32_e32 v218, 16, v18
	v_and_b32_e32 v219, 0xffff0000, v18
	v_lshlrev_b32_e32 v220, 16, v22
	v_and_b32_e32 v221, 0xffff0000, v22
	v_pk_add_f32 v[218:219], v[218:219], v[220:221]
	v_pk_add_f32 v[186:187], v[186:187], v[218:219]
	v_lshlrev_b32_e32 v218, 16, v19
	v_and_b32_e32 v219, 0xffff0000, v19
	v_lshlrev_b32_e32 v220, 16, v23
	v_and_b32_e32 v221, 0xffff0000, v23
	v_pk_add_f32 v[218:219], v[218:219], v[220:221]
	v_pk_add_f32 v[186:187], v[186:187], v[218:219]
	v_mov_b32_e32 v188, 0
	v_mov_b32_e32 v189, 0
	v_lshlrev_b32_e32 v218, 16, v24
	v_and_b32_e32 v219, 0xffff0000, v24
	v_lshlrev_b32_e32 v220, 16, v28
	v_and_b32_e32 v221, 0xffff0000, v28
	v_pk_add_f32 v[218:219], v[218:219], v[220:221]
	v_pk_add_f32 v[188:189], v[188:189], v[218:219]
	v_lshlrev_b32_e32 v218, 16, v25
	v_and_b32_e32 v219, 0xffff0000, v25
	v_lshlrev_b32_e32 v220, 16, v29
	v_and_b32_e32 v221, 0xffff0000, v29
	v_pk_add_f32 v[218:219], v[218:219], v[220:221]
	v_pk_add_f32 v[188:189], v[188:189], v[218:219]
	v_lshlrev_b32_e32 v218, 16, v26
	v_and_b32_e32 v219, 0xffff0000, v26
	v_lshlrev_b32_e32 v220, 16, v30
	v_and_b32_e32 v221, 0xffff0000, v30
	v_pk_add_f32 v[218:219], v[218:219], v[220:221]
	v_pk_add_f32 v[188:189], v[188:189], v[218:219]
	v_lshlrev_b32_e32 v218, 16, v27
	v_and_b32_e32 v219, 0xffff0000, v27
	v_lshlrev_b32_e32 v220, 16, v31
	v_and_b32_e32 v221, 0xffff0000, v31
	v_pk_add_f32 v[218:219], v[218:219], v[220:221]
	v_pk_add_f32 v[188:189], v[188:189], v[218:219]
	v_mov_b32_e32 v190, 0
	v_mov_b32_e32 v191, 0
	v_lshlrev_b32_e32 v218, 16, v36
	v_and_b32_e32 v219, 0xffff0000, v36
	v_lshlrev_b32_e32 v220, 16, v40
	v_and_b32_e32 v221, 0xffff0000, v40
	v_pk_add_f32 v[218:219], v[218:219], v[220:221]
	v_pk_add_f32 v[190:191], v[190:191], v[218:219]
	v_lshlrev_b32_e32 v218, 16, v37
	v_and_b32_e32 v219, 0xffff0000, v37
	v_lshlrev_b32_e32 v220, 16, v41
	v_and_b32_e32 v221, 0xffff0000, v41
	v_pk_add_f32 v[218:219], v[218:219], v[220:221]
	v_pk_add_f32 v[190:191], v[190:191], v[218:219]
	v_lshlrev_b32_e32 v218, 16, v38
	v_and_b32_e32 v219, 0xffff0000, v38
	v_lshlrev_b32_e32 v220, 16, v42
	v_and_b32_e32 v221, 0xffff0000, v42
	v_pk_add_f32 v[218:219], v[218:219], v[220:221]
	v_pk_add_f32 v[190:191], v[190:191], v[218:219]
	v_lshlrev_b32_e32 v218, 16, v39
	v_and_b32_e32 v219, 0xffff0000, v39
	v_lshlrev_b32_e32 v220, 16, v43
	v_and_b32_e32 v221, 0xffff0000, v43
	v_pk_add_f32 v[218:219], v[218:219], v[220:221]
	v_pk_add_f32 v[190:191], v[190:191], v[218:219]
	v_mov_b32_e32 v192, 0
	v_mov_b32_e32 v193, 0
	v_lshlrev_b32_e32 v218, 16, v44
	v_and_b32_e32 v219, 0xffff0000, v44
	v_lshlrev_b32_e32 v220, 16, v48
	v_and_b32_e32 v221, 0xffff0000, v48
	v_pk_add_f32 v[218:219], v[218:219], v[220:221]
	v_pk_add_f32 v[192:193], v[192:193], v[218:219]
	v_lshlrev_b32_e32 v218, 16, v45
	v_and_b32_e32 v219, 0xffff0000, v45
	v_lshlrev_b32_e32 v220, 16, v49
	v_and_b32_e32 v221, 0xffff0000, v49
	v_pk_add_f32 v[218:219], v[218:219], v[220:221]
	v_pk_add_f32 v[192:193], v[192:193], v[218:219]
	v_lshlrev_b32_e32 v218, 16, v46
	v_and_b32_e32 v219, 0xffff0000, v46
	v_lshlrev_b32_e32 v220, 16, v50
	v_and_b32_e32 v221, 0xffff0000, v50
	v_pk_add_f32 v[218:219], v[218:219], v[220:221]
	v_pk_add_f32 v[192:193], v[192:193], v[218:219]
	v_lshlrev_b32_e32 v218, 16, v47
	v_and_b32_e32 v219, 0xffff0000, v47
	v_lshlrev_b32_e32 v220, 16, v51
	v_and_b32_e32 v221, 0xffff0000, v51
	v_pk_add_f32 v[218:219], v[218:219], v[220:221]
	v_pk_add_f32 v[192:193], v[192:193], v[218:219]
	v_mov_b32_e32 v194, 0
	v_mov_b32_e32 v195, 0
	v_lshlrev_b32_e32 v218, 16, v52
	v_and_b32_e32 v219, 0xffff0000, v52
	v_lshlrev_b32_e32 v220, 16, v56
	v_and_b32_e32 v221, 0xffff0000, v56
	v_pk_add_f32 v[218:219], v[218:219], v[220:221]
	v_pk_add_f32 v[194:195], v[194:195], v[218:219]
	v_lshlrev_b32_e32 v218, 16, v53
	v_and_b32_e32 v219, 0xffff0000, v53
	v_lshlrev_b32_e32 v220, 16, v57
	v_and_b32_e32 v221, 0xffff0000, v57
	v_pk_add_f32 v[218:219], v[218:219], v[220:221]
	v_pk_add_f32 v[194:195], v[194:195], v[218:219]
	v_lshlrev_b32_e32 v218, 16, v54
	v_and_b32_e32 v219, 0xffff0000, v54
	v_lshlrev_b32_e32 v220, 16, v58
	v_and_b32_e32 v221, 0xffff0000, v58
	v_pk_add_f32 v[218:219], v[218:219], v[220:221]
	v_pk_add_f32 v[194:195], v[194:195], v[218:219]
	v_lshlrev_b32_e32 v218, 16, v55
	v_and_b32_e32 v219, 0xffff0000, v55
	v_lshlrev_b32_e32 v220, 16, v59
	v_and_b32_e32 v221, 0xffff0000, v59
	v_pk_add_f32 v[218:219], v[218:219], v[220:221]
	v_pk_add_f32 v[194:195], v[194:195], v[218:219]
	v_mov_b32_e32 v196, 0
	v_mov_b32_e32 v197, 0
	v_lshlrev_b32_e32 v218, 16, v60
	v_and_b32_e32 v219, 0xffff0000, v60
	v_lshlrev_b32_e32 v220, 16, v64
	v_and_b32_e32 v221, 0xffff0000, v64
	v_pk_add_f32 v[218:219], v[218:219], v[220:221]
	v_pk_add_f32 v[196:197], v[196:197], v[218:219]
	v_lshlrev_b32_e32 v218, 16, v61
	v_and_b32_e32 v219, 0xffff0000, v61
	v_lshlrev_b32_e32 v220, 16, v65
	v_and_b32_e32 v221, 0xffff0000, v65
	v_pk_add_f32 v[218:219], v[218:219], v[220:221]
	v_pk_add_f32 v[196:197], v[196:197], v[218:219]
	v_lshlrev_b32_e32 v218, 16, v62
	v_and_b32_e32 v219, 0xffff0000, v62
	v_lshlrev_b32_e32 v220, 16, v66
	v_and_b32_e32 v221, 0xffff0000, v66
	v_pk_add_f32 v[218:219], v[218:219], v[220:221]
	v_pk_add_f32 v[196:197], v[196:197], v[218:219]
	v_lshlrev_b32_e32 v218, 16, v63
	v_and_b32_e32 v219, 0xffff0000, v63
	v_lshlrev_b32_e32 v220, 16, v67
	v_and_b32_e32 v221, 0xffff0000, v67
	v_pk_add_f32 v[218:219], v[218:219], v[220:221]
	v_pk_add_f32 v[196:197], v[196:197], v[218:219]
	v_mov_b32_e32 v198, 0
	v_mov_b32_e32 v199, 0
	v_lshlrev_b32_e32 v218, 16, v68
	v_and_b32_e32 v219, 0xffff0000, v68
	v_lshlrev_b32_e32 v220, 16, v72
	v_and_b32_e32 v221, 0xffff0000, v72
	v_pk_add_f32 v[218:219], v[218:219], v[220:221]
	v_pk_add_f32 v[198:199], v[198:199], v[218:219]
	v_lshlrev_b32_e32 v218, 16, v69
	v_and_b32_e32 v219, 0xffff0000, v69
	v_lshlrev_b32_e32 v220, 16, v73
	v_and_b32_e32 v221, 0xffff0000, v73
	v_pk_add_f32 v[218:219], v[218:219], v[220:221]
	v_pk_add_f32 v[198:199], v[198:199], v[218:219]
	v_lshlrev_b32_e32 v218, 16, v70
	v_and_b32_e32 v219, 0xffff0000, v70
	v_lshlrev_b32_e32 v220, 16, v74
	v_and_b32_e32 v221, 0xffff0000, v74
	v_pk_add_f32 v[218:219], v[218:219], v[220:221]
	v_pk_add_f32 v[198:199], v[198:199], v[218:219]
	v_lshlrev_b32_e32 v218, 16, v71
	v_and_b32_e32 v219, 0xffff0000, v71
	v_lshlrev_b32_e32 v220, 16, v75
	v_and_b32_e32 v221, 0xffff0000, v75
	v_pk_add_f32 v[218:219], v[218:219], v[220:221]
	v_pk_add_f32 v[198:199], v[198:199], v[218:219]
	v_mov_b32_e32 v200, 0
	v_mov_b32_e32 v201, 0
	v_lshlrev_b32_e32 v218, 16, v76
	v_and_b32_e32 v219, 0xffff0000, v76
	v_lshlrev_b32_e32 v220, 16, v80
	v_and_b32_e32 v221, 0xffff0000, v80
	v_pk_add_f32 v[218:219], v[218:219], v[220:221]
	v_pk_add_f32 v[200:201], v[200:201], v[218:219]
	v_lshlrev_b32_e32 v218, 16, v77
	v_and_b32_e32 v219, 0xffff0000, v77
	v_lshlrev_b32_e32 v220, 16, v81
	v_and_b32_e32 v221, 0xffff0000, v81
	v_pk_add_f32 v[218:219], v[218:219], v[220:221]
	v_pk_add_f32 v[200:201], v[200:201], v[218:219]
	v_lshlrev_b32_e32 v218, 16, v78
	v_and_b32_e32 v219, 0xffff0000, v78
	v_lshlrev_b32_e32 v220, 16, v82
	v_and_b32_e32 v221, 0xffff0000, v82
	v_pk_add_f32 v[218:219], v[218:219], v[220:221]
	v_pk_add_f32 v[200:201], v[200:201], v[218:219]
	v_lshlrev_b32_e32 v218, 16, v79
	v_and_b32_e32 v219, 0xffff0000, v79
	v_lshlrev_b32_e32 v220, 16, v83
	v_and_b32_e32 v221, 0xffff0000, v83
	v_pk_add_f32 v[218:219], v[218:219], v[220:221]
	v_pk_add_f32 v[200:201], v[200:201], v[218:219]
	v_add_f32_e32 v202, v186, v187
	v_add_f32_e32 v203, v188, v189
	v_add_f32_e32 v204, v190, v191
	v_add_f32_e32 v205, v192, v193
	v_add_f32_e32 v206, v194, v195
	v_add_f32_e32 v207, v196, v197
	v_add_f32_e32 v208, v198, v199
	v_add_f32_e32 v209, v200, v201
	v_xor_b32_e32 v229, 4, v228
	ds_bpermute_b32 v210, v229, v202
	ds_bpermute_b32 v211, v229, v203
	ds_bpermute_b32 v212, v229, v204
	ds_bpermute_b32 v213, v229, v205
	ds_bpermute_b32 v214, v229, v206
	ds_bpermute_b32 v215, v229, v207
	ds_bpermute_b32 v216, v229, v208
	ds_bpermute_b32 v217, v229, v209
	s_waitcnt lgkmcnt(0)
	v_add_f32_e32 v202, v202, v210
	v_add_f32_e32 v203, v203, v211
	v_add_f32_e32 v204, v204, v212
	v_add_f32_e32 v205, v205, v213
	v_add_f32_e32 v206, v206, v214
	v_add_f32_e32 v207, v207, v215
	v_add_f32_e32 v208, v208, v216
	v_add_f32_e32 v209, v209, v217
	v_xor_b32_e32 v229, 8, v228
	ds_bpermute_b32 v210, v229, v202
	ds_bpermute_b32 v211, v229, v203
	ds_bpermute_b32 v212, v229, v204
	ds_bpermute_b32 v213, v229, v205
	ds_bpermute_b32 v214, v229, v206
	ds_bpermute_b32 v215, v229, v207
	ds_bpermute_b32 v216, v229, v208
	ds_bpermute_b32 v217, v229, v209
	s_waitcnt lgkmcnt(0)
	v_add_f32_e32 v202, v202, v210
	v_add_f32_e32 v203, v203, v211
	v_add_f32_e32 v204, v204, v212
	v_add_f32_e32 v205, v205, v213
	v_add_f32_e32 v206, v206, v214
	v_add_f32_e32 v207, v207, v215
	v_add_f32_e32 v208, v208, v216
	v_add_f32_e32 v209, v209, v217
	v_xor_b32_e32 v229, 16, v228
	ds_bpermute_b32 v210, v229, v202
	ds_bpermute_b32 v211, v229, v203
	ds_bpermute_b32 v212, v229, v204
	ds_bpermute_b32 v213, v229, v205
	ds_bpermute_b32 v214, v229, v206
	ds_bpermute_b32 v215, v229, v207
	ds_bpermute_b32 v216, v229, v208
	ds_bpermute_b32 v217, v229, v209
	s_waitcnt lgkmcnt(0)
	v_add_f32_e32 v202, v202, v210
	v_add_f32_e32 v203, v203, v211
	v_add_f32_e32 v204, v204, v212
	v_add_f32_e32 v205, v205, v213
	v_add_f32_e32 v206, v206, v214
	v_add_f32_e32 v207, v207, v215
	v_add_f32_e32 v208, v208, v216
	v_add_f32_e32 v209, v209, v217
	v_xor_b32_e32 v229, 32, v228
	ds_bpermute_b32 v210, v229, v202
	ds_bpermute_b32 v211, v229, v203
	ds_bpermute_b32 v212, v229, v204
	ds_bpermute_b32 v213, v229, v205
	ds_bpermute_b32 v214, v229, v206
	ds_bpermute_b32 v215, v229, v207
	ds_bpermute_b32 v216, v229, v208
	ds_bpermute_b32 v217, v229, v209
	s_waitcnt lgkmcnt(0)
	v_add_f32_e32 v202, v202, v210
	v_add_f32_e32 v203, v203, v211
	v_add_f32_e32 v204, v204, v212
	v_add_f32_e32 v205, v205, v213
	v_add_f32_e32 v206, v206, v214
	v_add_f32_e32 v207, v207, v215
	v_add_f32_e32 v208, v208, v216
	v_add_f32_e32 v209, v209, v217
	v_xor_b32_e32 v229, 64, v228
	ds_bpermute_b32 v210, v229, v202
	ds_bpermute_b32 v211, v229, v203
	ds_bpermute_b32 v212, v229, v204
	ds_bpermute_b32 v213, v229, v205
	ds_bpermute_b32 v214, v229, v206
	ds_bpermute_b32 v215, v229, v207
	ds_bpermute_b32 v216, v229, v208
	ds_bpermute_b32 v217, v229, v209
	s_waitcnt lgkmcnt(0)
	v_add_f32_e32 v202, v202, v210
	v_add_f32_e32 v203, v203, v211
	v_add_f32_e32 v204, v204, v212
	v_add_f32_e32 v205, v205, v213
	v_add_f32_e32 v206, v206, v214
	v_add_f32_e32 v207, v207, v215
	v_add_f32_e32 v208, v208, v216
	v_add_f32_e32 v209, v209, v217
	v_xor_b32_e32 v229, 128, v228
	ds_bpermute_b32 v210, v229, v202
	ds_bpermute_b32 v211, v229, v203
	ds_bpermute_b32 v212, v229, v204
	ds_bpermute_b32 v213, v229, v205
	ds_bpermute_b32 v214, v229, v206
	ds_bpermute_b32 v215, v229, v207
	ds_bpermute_b32 v216, v229, v208
	ds_bpermute_b32 v217, v229, v209
	s_waitcnt lgkmcnt(0)
	v_add_f32_e32 v202, v202, v210
	v_add_f32_e32 v203, v203, v211
	v_add_f32_e32 v204, v204, v212
	v_add_f32_e32 v205, v205, v213
	v_add_f32_e32 v206, v206, v214
	v_add_f32_e32 v207, v207, v215
	v_add_f32_e32 v208, v208, v216
	v_add_f32_e32 v209, v209, v217
	v_mov_b32_e32 v224, 0x3a800000
	v_mul_f32_e32 v202, v202, v224
	v_mul_f32_e32 v203, v203, v224
	v_mul_f32_e32 v204, v204, v224
	v_mul_f32_e32 v205, v205, v224
	v_mul_f32_e32 v206, v206, v224
	v_mul_f32_e32 v207, v207, v224
	v_mul_f32_e32 v208, v208, v224
	v_mul_f32_e32 v209, v209, v224
	v_mov_b32_e32 v186, 0
	v_mov_b32_e32 v187, 0
	v_lshlrev_b32_e32 v218, 16, v16
	v_and_b32_e32 v219, 0xffff0000, v16
	v_lshlrev_b32_e32 v220, 16, v20
	v_and_b32_e32 v221, 0xffff0000, v20
	v_pk_add_f32 v[218:219], v[218:219], v[202:203] op_sel_hi:[1,0] neg_lo:[0,1] neg_hi:[0,1]
	v_pk_add_f32 v[220:221], v[220:221], v[202:203] op_sel_hi:[1,0] neg_lo:[0,1] neg_hi:[0,1]
	v_pk_mul_f32 v[220:221], v[220:221], v[220:221]
	v_pk_fma_f32 v[220:221], v[218:219], v[218:219], v[220:221]
	v_pk_add_f32 v[186:187], v[186:187], v[220:221]
	v_lshlrev_b32_e32 v218, 16, v17
	v_and_b32_e32 v219, 0xffff0000, v17
	v_lshlrev_b32_e32 v220, 16, v21
	v_and_b32_e32 v221, 0xffff0000, v21
	v_pk_add_f32 v[218:219], v[218:219], v[202:203] op_sel_hi:[1,0] neg_lo:[0,1] neg_hi:[0,1]
	v_pk_add_f32 v[220:221], v[220:221], v[202:203] op_sel_hi:[1,0] neg_lo:[0,1] neg_hi:[0,1]
	v_pk_mul_f32 v[220:221], v[220:221], v[220:221]
	v_pk_fma_f32 v[220:221], v[218:219], v[218:219], v[220:221]
	v_pk_add_f32 v[186:187], v[186:187], v[220:221]
	v_lshlrev_b32_e32 v218, 16, v18
	v_and_b32_e32 v219, 0xffff0000, v18
	v_lshlrev_b32_e32 v220, 16, v22
	v_and_b32_e32 v221, 0xffff0000, v22
	v_pk_add_f32 v[218:219], v[218:219], v[202:203] op_sel_hi:[1,0] neg_lo:[0,1] neg_hi:[0,1]
	v_pk_add_f32 v[220:221], v[220:221], v[202:203] op_sel_hi:[1,0] neg_lo:[0,1] neg_hi:[0,1]
	v_pk_mul_f32 v[220:221], v[220:221], v[220:221]
	v_pk_fma_f32 v[220:221], v[218:219], v[218:219], v[220:221]
	v_pk_add_f32 v[186:187], v[186:187], v[220:221]
	v_lshlrev_b32_e32 v218, 16, v19
	v_and_b32_e32 v219, 0xffff0000, v19
	v_lshlrev_b32_e32 v220, 16, v23
	v_and_b32_e32 v221, 0xffff0000, v23
	v_pk_add_f32 v[218:219], v[218:219], v[202:203] op_sel_hi:[1,0] neg_lo:[0,1] neg_hi:[0,1]
	v_pk_add_f32 v[220:221], v[220:221], v[202:203] op_sel_hi:[1,0] neg_lo:[0,1] neg_hi:[0,1]
	v_pk_mul_f32 v[220:221], v[220:221], v[220:221]
	v_pk_fma_f32 v[220:221], v[218:219], v[218:219], v[220:221]
	v_pk_add_f32 v[186:187], v[186:187], v[220:221]
	v_mov_b32_e32 v188, 0
	v_mov_b32_e32 v189, 0
	v_lshlrev_b32_e32 v218, 16, v24
	v_and_b32_e32 v219, 0xffff0000, v24
	v_lshlrev_b32_e32 v220, 16, v28
	v_and_b32_e32 v221, 0xffff0000, v28
	v_pk_add_f32 v[218:219], v[218:219], v[202:203] op_sel:[0,1] neg_lo:[0,1] neg_hi:[0,1]
	v_pk_add_f32 v[220:221], v[220:221], v[202:203] op_sel:[0,1] neg_lo:[0,1] neg_hi:[0,1]
	v_pk_mul_f32 v[220:221], v[220:221], v[220:221]
	v_pk_fma_f32 v[220:221], v[218:219], v[218:219], v[220:221]
	v_pk_add_f32 v[188:189], v[188:189], v[220:221]
	v_lshlrev_b32_e32 v218, 16, v25
	v_and_b32_e32 v219, 0xffff0000, v25
	v_lshlrev_b32_e32 v220, 16, v29
	v_and_b32_e32 v221, 0xffff0000, v29
	v_pk_add_f32 v[218:219], v[218:219], v[202:203] op_sel:[0,1] neg_lo:[0,1] neg_hi:[0,1]
	v_pk_add_f32 v[220:221], v[220:221], v[202:203] op_sel:[0,1] neg_lo:[0,1] neg_hi:[0,1]
	v_pk_mul_f32 v[220:221], v[220:221], v[220:221]
	v_pk_fma_f32 v[220:221], v[218:219], v[218:219], v[220:221]
	v_pk_add_f32 v[188:189], v[188:189], v[220:221]
	v_lshlrev_b32_e32 v218, 16, v26
	v_and_b32_e32 v219, 0xffff0000, v26
	v_lshlrev_b32_e32 v220, 16, v30
	v_and_b32_e32 v221, 0xffff0000, v30
	v_pk_add_f32 v[218:219], v[218:219], v[202:203] op_sel:[0,1] neg_lo:[0,1] neg_hi:[0,1]
	v_pk_add_f32 v[220:221], v[220:221], v[202:203] op_sel:[0,1] neg_lo:[0,1] neg_hi:[0,1]
	v_pk_mul_f32 v[220:221], v[220:221], v[220:221]
	v_pk_fma_f32 v[220:221], v[218:219], v[218:219], v[220:221]
	v_pk_add_f32 v[188:189], v[188:189], v[220:221]
	v_lshlrev_b32_e32 v218, 16, v27
	v_and_b32_e32 v219, 0xffff0000, v27
	v_lshlrev_b32_e32 v220, 16, v31
	v_and_b32_e32 v221, 0xffff0000, v31
	v_pk_add_f32 v[218:219], v[218:219], v[202:203] op_sel:[0,1] neg_lo:[0,1] neg_hi:[0,1]
	v_pk_add_f32 v[220:221], v[220:221], v[202:203] op_sel:[0,1] neg_lo:[0,1] neg_hi:[0,1]
	v_pk_mul_f32 v[220:221], v[220:221], v[220:221]
	v_pk_fma_f32 v[220:221], v[218:219], v[218:219], v[220:221]
	v_pk_add_f32 v[188:189], v[188:189], v[220:221]
	v_mov_b32_e32 v190, 0
	v_mov_b32_e32 v191, 0
	v_lshlrev_b32_e32 v218, 16, v36
	v_and_b32_e32 v219, 0xffff0000, v36
	v_lshlrev_b32_e32 v220, 16, v40
	v_and_b32_e32 v221, 0xffff0000, v40
	v_pk_add_f32 v[218:219], v[218:219], v[204:205] op_sel_hi:[1,0] neg_lo:[0,1] neg_hi:[0,1]
	v_pk_add_f32 v[220:221], v[220:221], v[204:205] op_sel_hi:[1,0] neg_lo:[0,1] neg_hi:[0,1]
	v_pk_mul_f32 v[220:221], v[220:221], v[220:221]
	v_pk_fma_f32 v[220:221], v[218:219], v[218:219], v[220:221]
	v_pk_add_f32 v[190:191], v[190:191], v[220:221]
	v_lshlrev_b32_e32 v218, 16, v37
	v_and_b32_e32 v219, 0xffff0000, v37
	v_lshlrev_b32_e32 v220, 16, v41
	v_and_b32_e32 v221, 0xffff0000, v41
	v_pk_add_f32 v[218:219], v[218:219], v[204:205] op_sel_hi:[1,0] neg_lo:[0,1] neg_hi:[0,1]
	v_pk_add_f32 v[220:221], v[220:221], v[204:205] op_sel_hi:[1,0] neg_lo:[0,1] neg_hi:[0,1]
	v_pk_mul_f32 v[220:221], v[220:221], v[220:221]
	v_pk_fma_f32 v[220:221], v[218:219], v[218:219], v[220:221]
	v_pk_add_f32 v[190:191], v[190:191], v[220:221]
	v_lshlrev_b32_e32 v218, 16, v38
	v_and_b32_e32 v219, 0xffff0000, v38
	v_lshlrev_b32_e32 v220, 16, v42
	v_and_b32_e32 v221, 0xffff0000, v42
	v_pk_add_f32 v[218:219], v[218:219], v[204:205] op_sel_hi:[1,0] neg_lo:[0,1] neg_hi:[0,1]
	v_pk_add_f32 v[220:221], v[220:221], v[204:205] op_sel_hi:[1,0] neg_lo:[0,1] neg_hi:[0,1]
	v_pk_mul_f32 v[220:221], v[220:221], v[220:221]
	v_pk_fma_f32 v[220:221], v[218:219], v[218:219], v[220:221]
	v_pk_add_f32 v[190:191], v[190:191], v[220:221]
	v_lshlrev_b32_e32 v218, 16, v39
	v_and_b32_e32 v219, 0xffff0000, v39
	v_lshlrev_b32_e32 v220, 16, v43
	v_and_b32_e32 v221, 0xffff0000, v43
	v_pk_add_f32 v[218:219], v[218:219], v[204:205] op_sel_hi:[1,0] neg_lo:[0,1] neg_hi:[0,1]
	v_pk_add_f32 v[220:221], v[220:221], v[204:205] op_sel_hi:[1,0] neg_lo:[0,1] neg_hi:[0,1]
	v_pk_mul_f32 v[220:221], v[220:221], v[220:221]
	v_pk_fma_f32 v[220:221], v[218:219], v[218:219], v[220:221]
	v_pk_add_f32 v[190:191], v[190:191], v[220:221]
	v_mov_b32_e32 v192, 0
	v_mov_b32_e32 v193, 0
	v_lshlrev_b32_e32 v218, 16, v44
	v_and_b32_e32 v219, 0xffff0000, v44
	v_lshlrev_b32_e32 v220, 16, v48
	v_and_b32_e32 v221, 0xffff0000, v48
	v_pk_add_f32 v[218:219], v[218:219], v[204:205] op_sel:[0,1] neg_lo:[0,1] neg_hi:[0,1]
	v_pk_add_f32 v[220:221], v[220:221], v[204:205] op_sel:[0,1] neg_lo:[0,1] neg_hi:[0,1]
	v_pk_mul_f32 v[220:221], v[220:221], v[220:221]
	v_pk_fma_f32 v[220:221], v[218:219], v[218:219], v[220:221]
	v_pk_add_f32 v[192:193], v[192:193], v[220:221]
	v_lshlrev_b32_e32 v218, 16, v45
	v_and_b32_e32 v219, 0xffff0000, v45
	v_lshlrev_b32_e32 v220, 16, v49
	v_and_b32_e32 v221, 0xffff0000, v49
	v_pk_add_f32 v[218:219], v[218:219], v[204:205] op_sel:[0,1] neg_lo:[0,1] neg_hi:[0,1]
	v_pk_add_f32 v[220:221], v[220:221], v[204:205] op_sel:[0,1] neg_lo:[0,1] neg_hi:[0,1]
	v_pk_mul_f32 v[220:221], v[220:221], v[220:221]
	v_pk_fma_f32 v[220:221], v[218:219], v[218:219], v[220:221]
	v_pk_add_f32 v[192:193], v[192:193], v[220:221]
	v_lshlrev_b32_e32 v218, 16, v46
	v_and_b32_e32 v219, 0xffff0000, v46
	v_lshlrev_b32_e32 v220, 16, v50
	v_and_b32_e32 v221, 0xffff0000, v50
	v_pk_add_f32 v[218:219], v[218:219], v[204:205] op_sel:[0,1] neg_lo:[0,1] neg_hi:[0,1]
	v_pk_add_f32 v[220:221], v[220:221], v[204:205] op_sel:[0,1] neg_lo:[0,1] neg_hi:[0,1]
	v_pk_mul_f32 v[220:221], v[220:221], v[220:221]
	v_pk_fma_f32 v[220:221], v[218:219], v[218:219], v[220:221]
	v_pk_add_f32 v[192:193], v[192:193], v[220:221]
	v_lshlrev_b32_e32 v218, 16, v47
	v_and_b32_e32 v219, 0xffff0000, v47
	v_lshlrev_b32_e32 v220, 16, v51
	v_and_b32_e32 v221, 0xffff0000, v51
	v_pk_add_f32 v[218:219], v[218:219], v[204:205] op_sel:[0,1] neg_lo:[0,1] neg_hi:[0,1]
	v_pk_add_f32 v[220:221], v[220:221], v[204:205] op_sel:[0,1] neg_lo:[0,1] neg_hi:[0,1]
	v_pk_mul_f32 v[220:221], v[220:221], v[220:221]
	v_pk_fma_f32 v[220:221], v[218:219], v[218:219], v[220:221]
	v_pk_add_f32 v[192:193], v[192:193], v[220:221]
	v_mov_b32_e32 v194, 0
	v_mov_b32_e32 v195, 0
	v_lshlrev_b32_e32 v218, 16, v52
	v_and_b32_e32 v219, 0xffff0000, v52
	v_lshlrev_b32_e32 v220, 16, v56
	v_and_b32_e32 v221, 0xffff0000, v56
	v_pk_add_f32 v[218:219], v[218:219], v[206:207] op_sel_hi:[1,0] neg_lo:[0,1] neg_hi:[0,1]
	v_pk_add_f32 v[220:221], v[220:221], v[206:207] op_sel_hi:[1,0] neg_lo:[0,1] neg_hi:[0,1]
	v_pk_mul_f32 v[220:221], v[220:221], v[220:221]
	v_pk_fma_f32 v[220:221], v[218:219], v[218:219], v[220:221]
	v_pk_add_f32 v[194:195], v[194:195], v[220:221]
	v_lshlrev_b32_e32 v218, 16, v53
	v_and_b32_e32 v219, 0xffff0000, v53
	v_lshlrev_b32_e32 v220, 16, v57
	v_and_b32_e32 v221, 0xffff0000, v57
	v_pk_add_f32 v[218:219], v[218:219], v[206:207] op_sel_hi:[1,0] neg_lo:[0,1] neg_hi:[0,1]
	v_pk_add_f32 v[220:221], v[220:221], v[206:207] op_sel_hi:[1,0] neg_lo:[0,1] neg_hi:[0,1]
	v_pk_mul_f32 v[220:221], v[220:221], v[220:221]
	v_pk_fma_f32 v[220:221], v[218:219], v[218:219], v[220:221]
	v_pk_add_f32 v[194:195], v[194:195], v[220:221]
	v_lshlrev_b32_e32 v218, 16, v54
	v_and_b32_e32 v219, 0xffff0000, v54
	v_lshlrev_b32_e32 v220, 16, v58
	v_and_b32_e32 v221, 0xffff0000, v58
	v_pk_add_f32 v[218:219], v[218:219], v[206:207] op_sel_hi:[1,0] neg_lo:[0,1] neg_hi:[0,1]
	v_pk_add_f32 v[220:221], v[220:221], v[206:207] op_sel_hi:[1,0] neg_lo:[0,1] neg_hi:[0,1]
	v_pk_mul_f32 v[220:221], v[220:221], v[220:221]
	v_pk_fma_f32 v[220:221], v[218:219], v[218:219], v[220:221]
	v_pk_add_f32 v[194:195], v[194:195], v[220:221]
	v_lshlrev_b32_e32 v218, 16, v55
	v_and_b32_e32 v219, 0xffff0000, v55
	v_lshlrev_b32_e32 v220, 16, v59
	v_and_b32_e32 v221, 0xffff0000, v59
	v_pk_add_f32 v[218:219], v[218:219], v[206:207] op_sel_hi:[1,0] neg_lo:[0,1] neg_hi:[0,1]
	v_pk_add_f32 v[220:221], v[220:221], v[206:207] op_sel_hi:[1,0] neg_lo:[0,1] neg_hi:[0,1]
	v_pk_mul_f32 v[220:221], v[220:221], v[220:221]
	v_pk_fma_f32 v[220:221], v[218:219], v[218:219], v[220:221]
	v_pk_add_f32 v[194:195], v[194:195], v[220:221]
	v_mov_b32_e32 v196, 0
	v_mov_b32_e32 v197, 0
	v_lshlrev_b32_e32 v218, 16, v60
	v_and_b32_e32 v219, 0xffff0000, v60
	v_lshlrev_b32_e32 v220, 16, v64
	v_and_b32_e32 v221, 0xffff0000, v64
	v_pk_add_f32 v[218:219], v[218:219], v[206:207] op_sel:[0,1] neg_lo:[0,1] neg_hi:[0,1]
	v_pk_add_f32 v[220:221], v[220:221], v[206:207] op_sel:[0,1] neg_lo:[0,1] neg_hi:[0,1]
	v_pk_mul_f32 v[220:221], v[220:221], v[220:221]
	v_pk_fma_f32 v[220:221], v[218:219], v[218:219], v[220:221]
	v_pk_add_f32 v[196:197], v[196:197], v[220:221]
	v_lshlrev_b32_e32 v218, 16, v61
	v_and_b32_e32 v219, 0xffff0000, v61
	v_lshlrev_b32_e32 v220, 16, v65
	v_and_b32_e32 v221, 0xffff0000, v65
	v_pk_add_f32 v[218:219], v[218:219], v[206:207] op_sel:[0,1] neg_lo:[0,1] neg_hi:[0,1]
	v_pk_add_f32 v[220:221], v[220:221], v[206:207] op_sel:[0,1] neg_lo:[0,1] neg_hi:[0,1]
	v_pk_mul_f32 v[220:221], v[220:221], v[220:221]
	v_pk_fma_f32 v[220:221], v[218:219], v[218:219], v[220:221]
	v_pk_add_f32 v[196:197], v[196:197], v[220:221]
	v_lshlrev_b32_e32 v218, 16, v62
	v_and_b32_e32 v219, 0xffff0000, v62
	v_lshlrev_b32_e32 v220, 16, v66
	v_and_b32_e32 v221, 0xffff0000, v66
	v_pk_add_f32 v[218:219], v[218:219], v[206:207] op_sel:[0,1] neg_lo:[0,1] neg_hi:[0,1]
	v_pk_add_f32 v[220:221], v[220:221], v[206:207] op_sel:[0,1] neg_lo:[0,1] neg_hi:[0,1]
	v_pk_mul_f32 v[220:221], v[220:221], v[220:221]
	v_pk_fma_f32 v[220:221], v[218:219], v[218:219], v[220:221]
	v_pk_add_f32 v[196:197], v[196:197], v[220:221]
	v_lshlrev_b32_e32 v218, 16, v63
	v_and_b32_e32 v219, 0xffff0000, v63
	v_lshlrev_b32_e32 v220, 16, v67
	v_and_b32_e32 v221, 0xffff0000, v67
	v_pk_add_f32 v[218:219], v[218:219], v[206:207] op_sel:[0,1] neg_lo:[0,1] neg_hi:[0,1]
	v_pk_add_f32 v[220:221], v[220:221], v[206:207] op_sel:[0,1] neg_lo:[0,1] neg_hi:[0,1]
	v_pk_mul_f32 v[220:221], v[220:221], v[220:221]
	v_pk_fma_f32 v[220:221], v[218:219], v[218:219], v[220:221]
	v_pk_add_f32 v[196:197], v[196:197], v[220:221]
	v_mov_b32_e32 v198, 0
	v_mov_b32_e32 v199, 0
	v_lshlrev_b32_e32 v218, 16, v68
	v_and_b32_e32 v219, 0xffff0000, v68
	v_lshlrev_b32_e32 v220, 16, v72
	v_and_b32_e32 v221, 0xffff0000, v72
	v_pk_add_f32 v[218:219], v[218:219], v[208:209] op_sel_hi:[1,0] neg_lo:[0,1] neg_hi:[0,1]
	v_pk_add_f32 v[220:221], v[220:221], v[208:209] op_sel_hi:[1,0] neg_lo:[0,1] neg_hi:[0,1]
	v_pk_mul_f32 v[220:221], v[220:221], v[220:221]
	v_pk_fma_f32 v[220:221], v[218:219], v[218:219], v[220:221]
	v_pk_add_f32 v[198:199], v[198:199], v[220:221]
	v_lshlrev_b32_e32 v218, 16, v69
	v_and_b32_e32 v219, 0xffff0000, v69
	v_lshlrev_b32_e32 v220, 16, v73
	v_and_b32_e32 v221, 0xffff0000, v73
	v_pk_add_f32 v[218:219], v[218:219], v[208:209] op_sel_hi:[1,0] neg_lo:[0,1] neg_hi:[0,1]
	v_pk_add_f32 v[220:221], v[220:221], v[208:209] op_sel_hi:[1,0] neg_lo:[0,1] neg_hi:[0,1]
	v_pk_mul_f32 v[220:221], v[220:221], v[220:221]
	v_pk_fma_f32 v[220:221], v[218:219], v[218:219], v[220:221]
	v_pk_add_f32 v[198:199], v[198:199], v[220:221]
	v_lshlrev_b32_e32 v218, 16, v70
	v_and_b32_e32 v219, 0xffff0000, v70
	v_lshlrev_b32_e32 v220, 16, v74
	v_and_b32_e32 v221, 0xffff0000, v74
	v_pk_add_f32 v[218:219], v[218:219], v[208:209] op_sel_hi:[1,0] neg_lo:[0,1] neg_hi:[0,1]
	v_pk_add_f32 v[220:221], v[220:221], v[208:209] op_sel_hi:[1,0] neg_lo:[0,1] neg_hi:[0,1]
	v_pk_mul_f32 v[220:221], v[220:221], v[220:221]
	v_pk_fma_f32 v[220:221], v[218:219], v[218:219], v[220:221]
	v_pk_add_f32 v[198:199], v[198:199], v[220:221]
	v_lshlrev_b32_e32 v218, 16, v71
	v_and_b32_e32 v219, 0xffff0000, v71
	v_lshlrev_b32_e32 v220, 16, v75
	v_and_b32_e32 v221, 0xffff0000, v75
	v_pk_add_f32 v[218:219], v[218:219], v[208:209] op_sel_hi:[1,0] neg_lo:[0,1] neg_hi:[0,1]
	v_pk_add_f32 v[220:221], v[220:221], v[208:209] op_sel_hi:[1,0] neg_lo:[0,1] neg_hi:[0,1]
	v_pk_mul_f32 v[220:221], v[220:221], v[220:221]
	v_pk_fma_f32 v[220:221], v[218:219], v[218:219], v[220:221]
	v_pk_add_f32 v[198:199], v[198:199], v[220:221]
	v_mov_b32_e32 v200, 0
	v_mov_b32_e32 v201, 0
	v_lshlrev_b32_e32 v218, 16, v76
	v_and_b32_e32 v219, 0xffff0000, v76
	v_lshlrev_b32_e32 v220, 16, v80
	v_and_b32_e32 v221, 0xffff0000, v80
	v_pk_add_f32 v[218:219], v[218:219], v[208:209] op_sel:[0,1] neg_lo:[0,1] neg_hi:[0,1]
	v_pk_add_f32 v[220:221], v[220:221], v[208:209] op_sel:[0,1] neg_lo:[0,1] neg_hi:[0,1]
	v_pk_mul_f32 v[220:221], v[220:221], v[220:221]
	v_pk_fma_f32 v[220:221], v[218:219], v[218:219], v[220:221]
	v_pk_add_f32 v[200:201], v[200:201], v[220:221]
	v_lshlrev_b32_e32 v218, 16, v77
	v_and_b32_e32 v219, 0xffff0000, v77
	v_lshlrev_b32_e32 v220, 16, v81
	v_and_b32_e32 v221, 0xffff0000, v81
	v_pk_add_f32 v[218:219], v[218:219], v[208:209] op_sel:[0,1] neg_lo:[0,1] neg_hi:[0,1]
	v_pk_add_f32 v[220:221], v[220:221], v[208:209] op_sel:[0,1] neg_lo:[0,1] neg_hi:[0,1]
	v_pk_mul_f32 v[220:221], v[220:221], v[220:221]
	v_pk_fma_f32 v[220:221], v[218:219], v[218:219], v[220:221]
	v_pk_add_f32 v[200:201], v[200:201], v[220:221]
	v_lshlrev_b32_e32 v218, 16, v78
	v_and_b32_e32 v219, 0xffff0000, v78
	v_lshlrev_b32_e32 v220, 16, v82
	v_and_b32_e32 v221, 0xffff0000, v82
	v_pk_add_f32 v[218:219], v[218:219], v[208:209] op_sel:[0,1] neg_lo:[0,1] neg_hi:[0,1]
	v_pk_add_f32 v[220:221], v[220:221], v[208:209] op_sel:[0,1] neg_lo:[0,1] neg_hi:[0,1]
	v_pk_mul_f32 v[220:221], v[220:221], v[220:221]
	v_pk_fma_f32 v[220:221], v[218:219], v[218:219], v[220:221]
	v_pk_add_f32 v[200:201], v[200:201], v[220:221]
	v_lshlrev_b32_e32 v218, 16, v79
	v_and_b32_e32 v219, 0xffff0000, v79
	v_lshlrev_b32_e32 v220, 16, v83
	v_and_b32_e32 v221, 0xffff0000, v83
	v_pk_add_f32 v[218:219], v[218:219], v[208:209] op_sel:[0,1] neg_lo:[0,1] neg_hi:[0,1]
	v_pk_add_f32 v[220:221], v[220:221], v[208:209] op_sel:[0,1] neg_lo:[0,1] neg_hi:[0,1]
	v_pk_mul_f32 v[220:221], v[220:221], v[220:221]
	v_pk_fma_f32 v[220:221], v[218:219], v[218:219], v[220:221]
	v_pk_add_f32 v[200:201], v[200:201], v[220:221]
	v_add_f32_e32 v210, v186, v187
	v_add_f32_e32 v211, v188, v189
	v_add_f32_e32 v212, v190, v191
	v_add_f32_e32 v213, v192, v193
	v_add_f32_e32 v214, v194, v195
	v_add_f32_e32 v215, v196, v197
	v_add_f32_e32 v216, v198, v199
	v_add_f32_e32 v217, v200, v201
	v_xor_b32_e32 v229, 4, v228
	ds_bpermute_b32 v186, v229, v210
	ds_bpermute_b32 v187, v229, v211
	ds_bpermute_b32 v188, v229, v212
	ds_bpermute_b32 v189, v229, v213
	ds_bpermute_b32 v190, v229, v214
	ds_bpermute_b32 v191, v229, v215
	ds_bpermute_b32 v192, v229, v216
	ds_bpermute_b32 v193, v229, v217
	s_waitcnt lgkmcnt(0)
	v_add_f32_e32 v210, v210, v186
	v_add_f32_e32 v211, v211, v187
	v_add_f32_e32 v212, v212, v188
	v_add_f32_e32 v213, v213, v189
	v_add_f32_e32 v214, v214, v190
	v_add_f32_e32 v215, v215, v191
	v_add_f32_e32 v216, v216, v192
	v_add_f32_e32 v217, v217, v193
	v_xor_b32_e32 v229, 8, v228
	ds_bpermute_b32 v186, v229, v210
	ds_bpermute_b32 v187, v229, v211
	ds_bpermute_b32 v188, v229, v212
	ds_bpermute_b32 v189, v229, v213
	ds_bpermute_b32 v190, v229, v214
	ds_bpermute_b32 v191, v229, v215
	ds_bpermute_b32 v192, v229, v216
	ds_bpermute_b32 v193, v229, v217
	s_waitcnt lgkmcnt(0)
	v_add_f32_e32 v210, v210, v186
	v_add_f32_e32 v211, v211, v187
	v_add_f32_e32 v212, v212, v188
	v_add_f32_e32 v213, v213, v189
	v_add_f32_e32 v214, v214, v190
	v_add_f32_e32 v215, v215, v191
	v_add_f32_e32 v216, v216, v192
	v_add_f32_e32 v217, v217, v193
	v_xor_b32_e32 v229, 16, v228
	ds_bpermute_b32 v186, v229, v210
	ds_bpermute_b32 v187, v229, v211
	ds_bpermute_b32 v188, v229, v212
	ds_bpermute_b32 v189, v229, v213
	ds_bpermute_b32 v190, v229, v214
	ds_bpermute_b32 v191, v229, v215
	ds_bpermute_b32 v192, v229, v216
	ds_bpermute_b32 v193, v229, v217
	s_waitcnt lgkmcnt(0)
	v_add_f32_e32 v210, v210, v186
	v_add_f32_e32 v211, v211, v187
	v_add_f32_e32 v212, v212, v188
	v_add_f32_e32 v213, v213, v189
	v_add_f32_e32 v214, v214, v190
	v_add_f32_e32 v215, v215, v191
	v_add_f32_e32 v216, v216, v192
	v_add_f32_e32 v217, v217, v193
	v_xor_b32_e32 v229, 32, v228
	ds_bpermute_b32 v186, v229, v210
	ds_bpermute_b32 v187, v229, v211
	ds_bpermute_b32 v188, v229, v212
	ds_bpermute_b32 v189, v229, v213
	ds_bpermute_b32 v190, v229, v214
	ds_bpermute_b32 v191, v229, v215
	ds_bpermute_b32 v192, v229, v216
	ds_bpermute_b32 v193, v229, v217
	s_waitcnt lgkmcnt(0)
	v_add_f32_e32 v210, v210, v186
	v_add_f32_e32 v211, v211, v187
	v_add_f32_e32 v212, v212, v188
	v_add_f32_e32 v213, v213, v189
	v_add_f32_e32 v214, v214, v190
	v_add_f32_e32 v215, v215, v191
	v_add_f32_e32 v216, v216, v192
	v_add_f32_e32 v217, v217, v193
	v_xor_b32_e32 v229, 64, v228
	ds_bpermute_b32 v186, v229, v210
	ds_bpermute_b32 v187, v229, v211
	ds_bpermute_b32 v188, v229, v212
	ds_bpermute_b32 v189, v229, v213
	ds_bpermute_b32 v190, v229, v214
	ds_bpermute_b32 v191, v229, v215
	ds_bpermute_b32 v192, v229, v216
	ds_bpermute_b32 v193, v229, v217
	s_waitcnt lgkmcnt(0)
	v_add_f32_e32 v210, v210, v186
	v_add_f32_e32 v211, v211, v187
	v_add_f32_e32 v212, v212, v188
	v_add_f32_e32 v213, v213, v189
	v_add_f32_e32 v214, v214, v190
	v_add_f32_e32 v215, v215, v191
	v_add_f32_e32 v216, v216, v192
	v_add_f32_e32 v217, v217, v193
	v_xor_b32_e32 v229, 128, v228
	ds_bpermute_b32 v186, v229, v210
	ds_bpermute_b32 v187, v229, v211
	ds_bpermute_b32 v188, v229, v212
	ds_bpermute_b32 v189, v229, v213
	ds_bpermute_b32 v190, v229, v214
	ds_bpermute_b32 v191, v229, v215
	ds_bpermute_b32 v192, v229, v216
	ds_bpermute_b32 v193, v229, v217
	s_waitcnt lgkmcnt(0)
	v_add_f32_e32 v210, v210, v186
	v_add_f32_e32 v211, v211, v187
	v_add_f32_e32 v212, v212, v188
	v_add_f32_e32 v213, v213, v189
	v_add_f32_e32 v214, v214, v190
	v_add_f32_e32 v215, v215, v191
	v_add_f32_e32 v216, v216, v192
	v_add_f32_e32 v217, v217, v193
	v_mov_b32_e32 v225, 0x358637bd
	v_fma_f32 v210, v210, v224, v225
	v_rsq_f32_e32 v210, v210
	v_fma_f32 v211, v211, v224, v225
	v_rsq_f32_e32 v211, v211
	v_fma_f32 v212, v212, v224, v225
	v_rsq_f32_e32 v212, v212
	v_fma_f32 v213, v213, v224, v225
	v_rsq_f32_e32 v213, v213
	v_fma_f32 v214, v214, v224, v225
	v_rsq_f32_e32 v214, v214
	v_fma_f32 v215, v215, v224, v225
	v_rsq_f32_e32 v215, v215
	v_fma_f32 v216, v216, v224, v225
	v_rsq_f32_e32 v216, v216
	v_fma_f32 v217, v217, v224, v225
	v_rsq_f32_e32 v217, v217
	s_and_saveexec_b64 s[56:57], s[4:5]
	v_cndmask_b32_e64 v186, v20, v16, s[6:7]
	v_cndmask_b32_e64 v187, v21, v17, s[6:7]
	v_cndmask_b32_e64 v188, v22, v18, s[6:7]
	v_cndmask_b32_e64 v189, v23, v19, s[6:7]
	v_lshlrev_b32_e32 v222, 16, v186
	v_and_b32_e32 v223, 0xffff0000, v186
	v_pk_add_f32 v[222:223], v[222:223], v[202:203] op_sel_hi:[1,0] neg_lo:[0,1] neg_hi:[0,1]
	v_pk_mul_f32 v[222:223], v[222:223], v[210:211] op_sel_hi:[1,0]
	v_pk_fma_f32 v[222:223], v[222:223], v[0:1], v[8:9]
	v_cvt_pk_bf16_f32 v232, v222, v223
	v_lshlrev_b32_e32 v222, 16, v187
	v_and_b32_e32 v223, 0xffff0000, v187
	v_pk_add_f32 v[222:223], v[222:223], v[202:203] op_sel_hi:[1,0] neg_lo:[0,1] neg_hi:[0,1]
	v_pk_mul_f32 v[222:223], v[222:223], v[210:211] op_sel_hi:[1,0]
	v_pk_fma_f32 v[222:223], v[222:223], v[2:3], v[10:11]
	v_cvt_pk_bf16_f32 v233, v222, v223
	v_lshlrev_b32_e32 v222, 16, v188
	v_and_b32_e32 v223, 0xffff0000, v188
	v_pk_add_f32 v[222:223], v[222:223], v[202:203] op_sel_hi:[1,0] neg_lo:[0,1] neg_hi:[0,1]
	v_pk_mul_f32 v[222:223], v[222:223], v[210:211] op_sel_hi:[1,0]
	v_pk_fma_f32 v[222:223], v[222:223], v[4:5], v[12:13]
	v_cvt_pk_bf16_f32 v234, v222, v223
	v_lshlrev_b32_e32 v222, 16, v189
	v_and_b32_e32 v223, 0xffff0000, v189
	v_pk_add_f32 v[222:223], v[222:223], v[202:203] op_sel_hi:[1,0] neg_lo:[0,1] neg_hi:[0,1]
	v_pk_mul_f32 v[222:223], v[222:223], v[210:211] op_sel_hi:[1,0]
	v_pk_fma_f32 v[222:223], v[222:223], v[6:7], v[14:15]
	v_cvt_pk_bf16_f32 v235, v222, v223
	ds_write_b128 v107, v[232:235]
	v_cndmask_b32_e64 v186, v28, v24, s[6:7]
	v_cndmask_b32_e64 v187, v29, v25, s[6:7]
	v_cndmask_b32_e64 v188, v30, v26, s[6:7]
	v_cndmask_b32_e64 v189, v31, v27, s[6:7]
	v_lshlrev_b32_e32 v222, 16, v186
	v_and_b32_e32 v223, 0xffff0000, v186
	v_pk_add_f32 v[222:223], v[222:223], v[202:203] op_sel:[0,1] neg_lo:[0,1] neg_hi:[0,1]
	v_pk_mul_f32 v[222:223], v[222:223], v[210:211] op_sel:[0,1]
	v_pk_fma_f32 v[222:223], v[222:223], v[0:1], v[8:9]
	v_cvt_pk_bf16_f32 v236, v222, v223
	v_lshlrev_b32_e32 v222, 16, v187
	v_and_b32_e32 v223, 0xffff0000, v187
	v_pk_add_f32 v[222:223], v[222:223], v[202:203] op_sel:[0,1] neg_lo:[0,1] neg_hi:[0,1]
	v_pk_mul_f32 v[222:223], v[222:223], v[210:211] op_sel:[0,1]
	v_pk_fma_f32 v[222:223], v[222:223], v[2:3], v[10:11]
	v_cvt_pk_bf16_f32 v237, v222, v223
	v_lshlrev_b32_e32 v222, 16, v188
	v_and_b32_e32 v223, 0xffff0000, v188
	v_pk_add_f32 v[222:223], v[222:223], v[202:203] op_sel:[0,1] neg_lo:[0,1] neg_hi:[0,1]
	v_pk_mul_f32 v[222:223], v[222:223], v[210:211] op_sel:[0,1]
	v_pk_fma_f32 v[222:223], v[222:223], v[4:5], v[12:13]
	v_cvt_pk_bf16_f32 v238, v222, v223
	v_lshlrev_b32_e32 v222, 16, v189
	v_and_b32_e32 v223, 0xffff0000, v189
	v_pk_add_f32 v[222:223], v[222:223], v[202:203] op_sel:[0,1] neg_lo:[0,1] neg_hi:[0,1]
	v_pk_mul_f32 v[222:223], v[222:223], v[210:211] op_sel:[0,1]
	v_pk_fma_f32 v[222:223], v[222:223], v[6:7], v[14:15]
	v_cvt_pk_bf16_f32 v239, v222, v223
	ds_write_b128 v107, v[236:239] offset:528
	v_cndmask_b32_e64 v186, v40, v36, s[6:7]
	v_cndmask_b32_e64 v187, v41, v37, s[6:7]
	v_cndmask_b32_e64 v188, v42, v38, s[6:7]
	v_cndmask_b32_e64 v189, v43, v39, s[6:7]
	v_lshlrev_b32_e32 v222, 16, v186
	v_and_b32_e32 v223, 0xffff0000, v186
	v_pk_add_f32 v[222:223], v[222:223], v[204:205] op_sel_hi:[1,0] neg_lo:[0,1] neg_hi:[0,1]
	v_pk_mul_f32 v[222:223], v[222:223], v[212:213] op_sel_hi:[1,0]
	v_pk_fma_f32 v[222:223], v[222:223], v[0:1], v[8:9]
	v_cvt_pk_bf16_f32 v232, v222, v223
	v_lshlrev_b32_e32 v222, 16, v187
	v_and_b32_e32 v223, 0xffff0000, v187
	v_pk_add_f32 v[222:223], v[222:223], v[204:205] op_sel_hi:[1,0] neg_lo:[0,1] neg_hi:[0,1]
	v_pk_mul_f32 v[222:223], v[222:223], v[212:213] op_sel_hi:[1,0]
	v_pk_fma_f32 v[222:223], v[222:223], v[2:3], v[10:11]
	v_cvt_pk_bf16_f32 v233, v222, v223
	v_lshlrev_b32_e32 v222, 16, v188
	v_and_b32_e32 v223, 0xffff0000, v188
	v_pk_add_f32 v[222:223], v[222:223], v[204:205] op_sel_hi:[1,0] neg_lo:[0,1] neg_hi:[0,1]
	v_pk_mul_f32 v[222:223], v[222:223], v[212:213] op_sel_hi:[1,0]
	v_pk_fma_f32 v[222:223], v[222:223], v[4:5], v[12:13]
	v_cvt_pk_bf16_f32 v234, v222, v223
	v_lshlrev_b32_e32 v222, 16, v189
	v_and_b32_e32 v223, 0xffff0000, v189
	v_pk_add_f32 v[222:223], v[222:223], v[204:205] op_sel_hi:[1,0] neg_lo:[0,1] neg_hi:[0,1]
	v_pk_mul_f32 v[222:223], v[222:223], v[212:213] op_sel_hi:[1,0]
	v_pk_fma_f32 v[222:223], v[222:223], v[6:7], v[14:15]
	v_cvt_pk_bf16_f32 v235, v222, v223
	ds_write_b128 v107, v[232:235] offset:1056
	v_cndmask_b32_e64 v186, v48, v44, s[6:7]
	v_cndmask_b32_e64 v187, v49, v45, s[6:7]
	v_cndmask_b32_e64 v188, v50, v46, s[6:7]
	v_cndmask_b32_e64 v189, v51, v47, s[6:7]
	v_lshlrev_b32_e32 v222, 16, v186
	v_and_b32_e32 v223, 0xffff0000, v186
	v_pk_add_f32 v[222:223], v[222:223], v[204:205] op_sel:[0,1] neg_lo:[0,1] neg_hi:[0,1]
	v_pk_mul_f32 v[222:223], v[222:223], v[212:213] op_sel:[0,1]
	v_pk_fma_f32 v[222:223], v[222:223], v[0:1], v[8:9]
	v_cvt_pk_bf16_f32 v236, v222, v223
	v_lshlrev_b32_e32 v222, 16, v187
	v_and_b32_e32 v223, 0xffff0000, v187
	v_pk_add_f32 v[222:223], v[222:223], v[204:205] op_sel:[0,1] neg_lo:[0,1] neg_hi:[0,1]
	v_pk_mul_f32 v[222:223], v[222:223], v[212:213] op_sel:[0,1]
	v_pk_fma_f32 v[222:223], v[222:223], v[2:3], v[10:11]
	v_cvt_pk_bf16_f32 v237, v222, v223
	v_lshlrev_b32_e32 v222, 16, v188
	v_and_b32_e32 v223, 0xffff0000, v188
	v_pk_add_f32 v[222:223], v[222:223], v[204:205] op_sel:[0,1] neg_lo:[0,1] neg_hi:[0,1]
	v_pk_mul_f32 v[222:223], v[222:223], v[212:213] op_sel:[0,1]
	v_pk_fma_f32 v[222:223], v[222:223], v[4:5], v[12:13]
	v_cvt_pk_bf16_f32 v238, v222, v223
	v_lshlrev_b32_e32 v222, 16, v189
	v_and_b32_e32 v223, 0xffff0000, v189
	v_pk_add_f32 v[222:223], v[222:223], v[204:205] op_sel:[0,1] neg_lo:[0,1] neg_hi:[0,1]
	v_pk_mul_f32 v[222:223], v[222:223], v[212:213] op_sel:[0,1]
	v_pk_fma_f32 v[222:223], v[222:223], v[6:7], v[14:15]
	v_cvt_pk_bf16_f32 v239, v222, v223
	ds_write_b128 v107, v[236:239] offset:1584
	v_cndmask_b32_e64 v186, v56, v52, s[6:7]
	v_cndmask_b32_e64 v187, v57, v53, s[6:7]
	v_cndmask_b32_e64 v188, v58, v54, s[6:7]
	v_cndmask_b32_e64 v189, v59, v55, s[6:7]
	v_lshlrev_b32_e32 v222, 16, v186
	v_and_b32_e32 v223, 0xffff0000, v186
	v_pk_add_f32 v[222:223], v[222:223], v[206:207] op_sel_hi:[1,0] neg_lo:[0,1] neg_hi:[0,1]
	v_pk_mul_f32 v[222:223], v[222:223], v[214:215] op_sel_hi:[1,0]
	v_pk_fma_f32 v[222:223], v[222:223], v[0:1], v[8:9]
	v_cvt_pk_bf16_f32 v232, v222, v223
	v_lshlrev_b32_e32 v222, 16, v187
	v_and_b32_e32 v223, 0xffff0000, v187
	v_pk_add_f32 v[222:223], v[222:223], v[206:207] op_sel_hi:[1,0] neg_lo:[0,1] neg_hi:[0,1]
	v_pk_mul_f32 v[222:223], v[222:223], v[214:215] op_sel_hi:[1,0]
	v_pk_fma_f32 v[222:223], v[222:223], v[2:3], v[10:11]
	v_cvt_pk_bf16_f32 v233, v222, v223
	v_lshlrev_b32_e32 v222, 16, v188
	v_and_b32_e32 v223, 0xffff0000, v188
	v_pk_add_f32 v[222:223], v[222:223], v[206:207] op_sel_hi:[1,0] neg_lo:[0,1] neg_hi:[0,1]
	v_pk_mul_f32 v[222:223], v[222:223], v[214:215] op_sel_hi:[1,0]
	v_pk_fma_f32 v[222:223], v[222:223], v[4:5], v[12:13]
	v_cvt_pk_bf16_f32 v234, v222, v223
	v_lshlrev_b32_e32 v222, 16, v189
	v_and_b32_e32 v223, 0xffff0000, v189
	v_pk_add_f32 v[222:223], v[222:223], v[206:207] op_sel_hi:[1,0] neg_lo:[0,1] neg_hi:[0,1]
	v_pk_mul_f32 v[222:223], v[222:223], v[214:215] op_sel_hi:[1,0]
	v_pk_fma_f32 v[222:223], v[222:223], v[6:7], v[14:15]
	v_cvt_pk_bf16_f32 v235, v222, v223
	ds_write_b128 v107, v[232:235] offset:2112
	v_cndmask_b32_e64 v186, v64, v60, s[6:7]
	v_cndmask_b32_e64 v187, v65, v61, s[6:7]
	v_cndmask_b32_e64 v188, v66, v62, s[6:7]
	v_cndmask_b32_e64 v189, v67, v63, s[6:7]
	v_lshlrev_b32_e32 v222, 16, v186
	v_and_b32_e32 v223, 0xffff0000, v186
	v_pk_add_f32 v[222:223], v[222:223], v[206:207] op_sel:[0,1] neg_lo:[0,1] neg_hi:[0,1]
	v_pk_mul_f32 v[222:223], v[222:223], v[214:215] op_sel:[0,1]
	v_pk_fma_f32 v[222:223], v[222:223], v[0:1], v[8:9]
	v_cvt_pk_bf16_f32 v236, v222, v223
	v_lshlrev_b32_e32 v222, 16, v187
	v_and_b32_e32 v223, 0xffff0000, v187
	v_pk_add_f32 v[222:223], v[222:223], v[206:207] op_sel:[0,1] neg_lo:[0,1] neg_hi:[0,1]
	v_pk_mul_f32 v[222:223], v[222:223], v[214:215] op_sel:[0,1]
	v_pk_fma_f32 v[222:223], v[222:223], v[2:3], v[10:11]
	v_cvt_pk_bf16_f32 v237, v222, v223
	v_lshlrev_b32_e32 v222, 16, v188
	v_and_b32_e32 v223, 0xffff0000, v188
	v_pk_add_f32 v[222:223], v[222:223], v[206:207] op_sel:[0,1] neg_lo:[0,1] neg_hi:[0,1]
	v_pk_mul_f32 v[222:223], v[222:223], v[214:215] op_sel:[0,1]
	v_pk_fma_f32 v[222:223], v[222:223], v[4:5], v[12:13]
	v_cvt_pk_bf16_f32 v238, v222, v223
	v_lshlrev_b32_e32 v222, 16, v189
	v_and_b32_e32 v223, 0xffff0000, v189
	v_pk_add_f32 v[222:223], v[222:223], v[206:207] op_sel:[0,1] neg_lo:[0,1] neg_hi:[0,1]
	v_pk_mul_f32 v[222:223], v[222:223], v[214:215] op_sel:[0,1]
	v_pk_fma_f32 v[222:223], v[222:223], v[6:7], v[14:15]
	v_cvt_pk_bf16_f32 v239, v222, v223
	ds_write_b128 v107, v[236:239] offset:2640
	v_cndmask_b32_e64 v186, v72, v68, s[6:7]
	v_cndmask_b32_e64 v187, v73, v69, s[6:7]
	v_cndmask_b32_e64 v188, v74, v70, s[6:7]
	v_cndmask_b32_e64 v189, v75, v71, s[6:7]
	v_lshlrev_b32_e32 v222, 16, v186
	v_and_b32_e32 v223, 0xffff0000, v186
	v_pk_add_f32 v[222:223], v[222:223], v[208:209] op_sel_hi:[1,0] neg_lo:[0,1] neg_hi:[0,1]
	v_pk_mul_f32 v[222:223], v[222:223], v[216:217] op_sel_hi:[1,0]
	v_pk_fma_f32 v[222:223], v[222:223], v[0:1], v[8:9]
	v_cvt_pk_bf16_f32 v232, v222, v223
	v_lshlrev_b32_e32 v222, 16, v187
	v_and_b32_e32 v223, 0xffff0000, v187
	v_pk_add_f32 v[222:223], v[222:223], v[208:209] op_sel_hi:[1,0] neg_lo:[0,1] neg_hi:[0,1]
	v_pk_mul_f32 v[222:223], v[222:223], v[216:217] op_sel_hi:[1,0]
	v_pk_fma_f32 v[222:223], v[222:223], v[2:3], v[10:11]
	v_cvt_pk_bf16_f32 v233, v222, v223
	v_lshlrev_b32_e32 v222, 16, v188
	v_and_b32_e32 v223, 0xffff0000, v188
	v_pk_add_f32 v[222:223], v[222:223], v[208:209] op_sel_hi:[1,0] neg_lo:[0,1] neg_hi:[0,1]
	v_pk_mul_f32 v[222:223], v[222:223], v[216:217] op_sel_hi:[1,0]
	v_pk_fma_f32 v[222:223], v[222:223], v[4:5], v[12:13]
	v_cvt_pk_bf16_f32 v234, v222, v223
	v_lshlrev_b32_e32 v222, 16, v189
	v_and_b32_e32 v223, 0xffff0000, v189
	v_pk_add_f32 v[222:223], v[222:223], v[208:209] op_sel_hi:[1,0] neg_lo:[0,1] neg_hi:[0,1]
	v_pk_mul_f32 v[222:223], v[222:223], v[216:217] op_sel_hi:[1,0]
	v_pk_fma_f32 v[222:223], v[222:223], v[6:7], v[14:15]
	v_cvt_pk_bf16_f32 v235, v222, v223
	ds_write_b128 v107, v[232:235] offset:3168
	v_cndmask_b32_e64 v186, v80, v76, s[6:7]
	v_cndmask_b32_e64 v187, v81, v77, s[6:7]
	v_cndmask_b32_e64 v188, v82, v78, s[6:7]
	v_cndmask_b32_e64 v189, v83, v79, s[6:7]
	v_lshlrev_b32_e32 v222, 16, v186
	v_and_b32_e32 v223, 0xffff0000, v186
	v_pk_add_f32 v[222:223], v[222:223], v[208:209] op_sel:[0,1] neg_lo:[0,1] neg_hi:[0,1]
	v_pk_mul_f32 v[222:223], v[222:223], v[216:217] op_sel:[0,1]
	v_pk_fma_f32 v[222:223], v[222:223], v[0:1], v[8:9]
	v_cvt_pk_bf16_f32 v236, v222, v223
	v_lshlrev_b32_e32 v222, 16, v187
	v_and_b32_e32 v223, 0xffff0000, v187
	v_pk_add_f32 v[222:223], v[222:223], v[208:209] op_sel:[0,1] neg_lo:[0,1] neg_hi:[0,1]
	v_pk_mul_f32 v[222:223], v[222:223], v[216:217] op_sel:[0,1]
	v_pk_fma_f32 v[222:223], v[222:223], v[2:3], v[10:11]
	v_cvt_pk_bf16_f32 v237, v222, v223
	v_lshlrev_b32_e32 v222, 16, v188
	v_and_b32_e32 v223, 0xffff0000, v188
	v_pk_add_f32 v[222:223], v[222:223], v[208:209] op_sel:[0,1] neg_lo:[0,1] neg_hi:[0,1]
	v_pk_mul_f32 v[222:223], v[222:223], v[216:217] op_sel:[0,1]
	v_pk_fma_f32 v[222:223], v[222:223], v[4:5], v[12:13]
	v_cvt_pk_bf16_f32 v238, v222, v223
	v_lshlrev_b32_e32 v222, 16, v189
	v_and_b32_e32 v223, 0xffff0000, v189
	v_pk_add_f32 v[222:223], v[222:223], v[208:209] op_sel:[0,1] neg_lo:[0,1] neg_hi:[0,1]
	v_pk_mul_f32 v[222:223], v[222:223], v[216:217] op_sel:[0,1]
	v_pk_fma_f32 v[222:223], v[222:223], v[6:7], v[14:15]
	v_cvt_pk_bf16_f32 v239, v222, v223
	ds_write_b128 v107, v[236:239] offset:3696
	s_or_b64 exec, exec, s[56:57]
	s_waitcnt vmcnt(0)
	v_mov_b32_e32 v186, 0
	v_mov_b32_e32 v187, 0
	v_lshlrev_b32_e32 v218, 16, v84
	v_and_b32_e32 v219, 0xffff0000, v84
	v_lshlrev_b32_e32 v220, 16, v88
	v_and_b32_e32 v221, 0xffff0000, v88
	v_pk_add_f32 v[218:219], v[218:219], v[220:221]
	v_pk_add_f32 v[186:187], v[186:187], v[218:219]
	v_lshlrev_b32_e32 v218, 16, v85
	v_and_b32_e32 v219, 0xffff0000, v85
	v_lshlrev_b32_e32 v220, 16, v89
	v_and_b32_e32 v221, 0xffff0000, v89
	v_pk_add_f32 v[218:219], v[218:219], v[220:221]
	v_pk_add_f32 v[186:187], v[186:187], v[218:219]
	v_lshlrev_b32_e32 v218, 16, v86
	v_and_b32_e32 v219, 0xffff0000, v86
	v_lshlrev_b32_e32 v220, 16, v90
	v_and_b32_e32 v221, 0xffff0000, v90
	v_pk_add_f32 v[218:219], v[218:219], v[220:221]
	v_pk_add_f32 v[186:187], v[186:187], v[218:219]
	v_lshlrev_b32_e32 v218, 16, v87
	v_and_b32_e32 v219, 0xffff0000, v87
	v_lshlrev_b32_e32 v220, 16, v91
	v_and_b32_e32 v221, 0xffff0000, v91
	v_pk_add_f32 v[218:219], v[218:219], v[220:221]
	v_pk_add_f32 v[186:187], v[186:187], v[218:219]
	v_mov_b32_e32 v188, 0
	v_mov_b32_e32 v189, 0
	v_lshlrev_b32_e32 v218, 16, v92
	v_and_b32_e32 v219, 0xffff0000, v92
	v_lshlrev_b32_e32 v220, 16, v110
	v_and_b32_e32 v221, 0xffff0000, v110
	v_pk_add_f32 v[218:219], v[218:219], v[220:221]
	v_pk_add_f32 v[188:189], v[188:189], v[218:219]
	v_lshlrev_b32_e32 v218, 16, v93
	v_and_b32_e32 v219, 0xffff0000, v93
	v_lshlrev_b32_e32 v220, 16, v111
	v_and_b32_e32 v221, 0xffff0000, v111
	v_pk_add_f32 v[218:219], v[218:219], v[220:221]
	v_pk_add_f32 v[188:189], v[188:189], v[218:219]
	v_lshlrev_b32_e32 v218, 16, v94
	v_and_b32_e32 v219, 0xffff0000, v94
	v_lshlrev_b32_e32 v220, 16, v112
	v_and_b32_e32 v221, 0xffff0000, v112
	v_pk_add_f32 v[218:219], v[218:219], v[220:221]
	v_pk_add_f32 v[188:189], v[188:189], v[218:219]
	v_lshlrev_b32_e32 v218, 16, v95
	v_and_b32_e32 v219, 0xffff0000, v95
	v_lshlrev_b32_e32 v220, 16, v113
	v_and_b32_e32 v221, 0xffff0000, v113
	v_pk_add_f32 v[218:219], v[218:219], v[220:221]
	v_pk_add_f32 v[188:189], v[188:189], v[218:219]
	v_mov_b32_e32 v190, 0
	v_mov_b32_e32 v191, 0
	v_lshlrev_b32_e32 v218, 16, v114
	v_and_b32_e32 v219, 0xffff0000, v114
	v_lshlrev_b32_e32 v220, 16, v118
	v_and_b32_e32 v221, 0xffff0000, v118
	v_pk_add_f32 v[218:219], v[218:219], v[220:221]
	v_pk_add_f32 v[190:191], v[190:191], v[218:219]
	v_lshlrev_b32_e32 v218, 16, v115
	v_and_b32_e32 v219, 0xffff0000, v115
	v_lshlrev_b32_e32 v220, 16, v119
	v_and_b32_e32 v221, 0xffff0000, v119
	v_pk_add_f32 v[218:219], v[218:219], v[220:221]
	v_pk_add_f32 v[190:191], v[190:191], v[218:219]
	v_lshlrev_b32_e32 v218, 16, v116
	v_and_b32_e32 v219, 0xffff0000, v116
	v_lshlrev_b32_e32 v220, 16, v120
	v_and_b32_e32 v221, 0xffff0000, v120
	v_pk_add_f32 v[218:219], v[218:219], v[220:221]
	v_pk_add_f32 v[190:191], v[190:191], v[218:219]
	v_lshlrev_b32_e32 v218, 16, v117
	v_and_b32_e32 v219, 0xffff0000, v117
	v_lshlrev_b32_e32 v220, 16, v121
	v_and_b32_e32 v221, 0xffff0000, v121
	v_pk_add_f32 v[218:219], v[218:219], v[220:221]
	v_pk_add_f32 v[190:191], v[190:191], v[218:219]
	v_mov_b32_e32 v192, 0
	v_mov_b32_e32 v193, 0
	v_lshlrev_b32_e32 v218, 16, v122
	v_and_b32_e32 v219, 0xffff0000, v122
	v_lshlrev_b32_e32 v220, 16, v148
	v_and_b32_e32 v221, 0xffff0000, v148
	v_pk_add_f32 v[218:219], v[218:219], v[220:221]
	v_pk_add_f32 v[192:193], v[192:193], v[218:219]
	v_lshlrev_b32_e32 v218, 16, v123
	v_and_b32_e32 v219, 0xffff0000, v123
	v_lshlrev_b32_e32 v220, 16, v149
	v_and_b32_e32 v221, 0xffff0000, v149
	v_pk_add_f32 v[218:219], v[218:219], v[220:221]
	v_pk_add_f32 v[192:193], v[192:193], v[218:219]
	v_lshlrev_b32_e32 v218, 16, v124
	v_and_b32_e32 v219, 0xffff0000, v124
	v_lshlrev_b32_e32 v220, 16, v150
	v_and_b32_e32 v221, 0xffff0000, v150
	v_pk_add_f32 v[218:219], v[218:219], v[220:221]
	v_pk_add_f32 v[192:193], v[192:193], v[218:219]
	v_lshlrev_b32_e32 v218, 16, v125
	v_and_b32_e32 v219, 0xffff0000, v125
	v_lshlrev_b32_e32 v220, 16, v151
	v_and_b32_e32 v221, 0xffff0000, v151
	v_pk_add_f32 v[218:219], v[218:219], v[220:221]
	v_pk_add_f32 v[192:193], v[192:193], v[218:219]
	v_mov_b32_e32 v194, 0
	v_mov_b32_e32 v195, 0
	v_lshlrev_b32_e32 v218, 16, v152
	v_and_b32_e32 v219, 0xffff0000, v152
	v_lshlrev_b32_e32 v220, 16, v156
	v_and_b32_e32 v221, 0xffff0000, v156
	v_pk_add_f32 v[218:219], v[218:219], v[220:221]
	v_pk_add_f32 v[194:195], v[194:195], v[218:219]
	v_lshlrev_b32_e32 v218, 16, v153
	v_and_b32_e32 v219, 0xffff0000, v153
	v_lshlrev_b32_e32 v220, 16, v157
	v_and_b32_e32 v221, 0xffff0000, v157
	v_pk_add_f32 v[218:219], v[218:219], v[220:221]
	v_pk_add_f32 v[194:195], v[194:195], v[218:219]
	v_lshlrev_b32_e32 v218, 16, v154
	v_and_b32_e32 v219, 0xffff0000, v154
	v_lshlrev_b32_e32 v220, 16, v158
	v_and_b32_e32 v221, 0xffff0000, v158
	v_pk_add_f32 v[218:219], v[218:219], v[220:221]
	v_pk_add_f32 v[194:195], v[194:195], v[218:219]
	v_lshlrev_b32_e32 v218, 16, v155
	v_and_b32_e32 v219, 0xffff0000, v155
	v_lshlrev_b32_e32 v220, 16, v159
	v_and_b32_e32 v221, 0xffff0000, v159
	v_pk_add_f32 v[218:219], v[218:219], v[220:221]
	v_pk_add_f32 v[194:195], v[194:195], v[218:219]
	v_mov_b32_e32 v196, 0
	v_mov_b32_e32 v197, 0
	v_lshlrev_b32_e32 v218, 16, v160
	v_and_b32_e32 v219, 0xffff0000, v160
	v_lshlrev_b32_e32 v220, 16, v166
	v_and_b32_e32 v221, 0xffff0000, v166
	v_pk_add_f32 v[218:219], v[218:219], v[220:221]
	v_pk_add_f32 v[196:197], v[196:197], v[218:219]
	v_lshlrev_b32_e32 v218, 16, v161
	v_and_b32_e32 v219, 0xffff0000, v161
	v_lshlrev_b32_e32 v220, 16, v167
	v_and_b32_e32 v221, 0xffff0000, v167
	v_pk_add_f32 v[218:219], v[218:219], v[220:221]
	v_pk_add_f32 v[196:197], v[196:197], v[218:219]
	v_lshlrev_b32_e32 v218, 16, v162
	v_and_b32_e32 v219, 0xffff0000, v162
	v_lshlrev_b32_e32 v220, 16, v168
	v_and_b32_e32 v221, 0xffff0000, v168
	v_pk_add_f32 v[218:219], v[218:219], v[220:221]
	v_pk_add_f32 v[196:197], v[196:197], v[218:219]
	v_lshlrev_b32_e32 v218, 16, v163
	v_and_b32_e32 v219, 0xffff0000, v163
	v_lshlrev_b32_e32 v220, 16, v169
	v_and_b32_e32 v221, 0xffff0000, v169
	v_pk_add_f32 v[218:219], v[218:219], v[220:221]
	v_pk_add_f32 v[196:197], v[196:197], v[218:219]
	v_mov_b32_e32 v198, 0
	v_mov_b32_e32 v199, 0
	v_lshlrev_b32_e32 v218, 16, v170
	v_and_b32_e32 v219, 0xffff0000, v170
	v_lshlrev_b32_e32 v220, 16, v174
	v_and_b32_e32 v221, 0xffff0000, v174
	v_pk_add_f32 v[218:219], v[218:219], v[220:221]
	v_pk_add_f32 v[198:199], v[198:199], v[218:219]
	v_lshlrev_b32_e32 v218, 16, v171
	v_and_b32_e32 v219, 0xffff0000, v171
	v_lshlrev_b32_e32 v220, 16, v175
	v_and_b32_e32 v221, 0xffff0000, v175
	v_pk_add_f32 v[218:219], v[218:219], v[220:221]
	v_pk_add_f32 v[198:199], v[198:199], v[218:219]
	v_lshlrev_b32_e32 v218, 16, v172
	v_and_b32_e32 v219, 0xffff0000, v172
	v_lshlrev_b32_e32 v220, 16, v176
	v_and_b32_e32 v221, 0xffff0000, v176
	v_pk_add_f32 v[218:219], v[218:219], v[220:221]
	v_pk_add_f32 v[198:199], v[198:199], v[218:219]
	v_lshlrev_b32_e32 v218, 16, v173
	v_and_b32_e32 v219, 0xffff0000, v173
	v_lshlrev_b32_e32 v220, 16, v177
	v_and_b32_e32 v221, 0xffff0000, v177
	v_pk_add_f32 v[218:219], v[218:219], v[220:221]
	v_pk_add_f32 v[198:199], v[198:199], v[218:219]
	v_mov_b32_e32 v200, 0
	v_mov_b32_e32 v201, 0
	v_lshlrev_b32_e32 v218, 16, v178
	v_and_b32_e32 v219, 0xffff0000, v178
	v_lshlrev_b32_e32 v220, 16, v182
	v_and_b32_e32 v221, 0xffff0000, v182
	v_pk_add_f32 v[218:219], v[218:219], v[220:221]
	v_pk_add_f32 v[200:201], v[200:201], v[218:219]
	v_lshlrev_b32_e32 v218, 16, v179
	v_and_b32_e32 v219, 0xffff0000, v179
	v_lshlrev_b32_e32 v220, 16, v183
	v_and_b32_e32 v221, 0xffff0000, v183
	v_pk_add_f32 v[218:219], v[218:219], v[220:221]
	v_pk_add_f32 v[200:201], v[200:201], v[218:219]
	v_lshlrev_b32_e32 v218, 16, v180
	v_and_b32_e32 v219, 0xffff0000, v180
	v_lshlrev_b32_e32 v220, 16, v184
	v_and_b32_e32 v221, 0xffff0000, v184
	v_pk_add_f32 v[218:219], v[218:219], v[220:221]
	v_pk_add_f32 v[200:201], v[200:201], v[218:219]
	v_lshlrev_b32_e32 v218, 16, v181
	v_and_b32_e32 v219, 0xffff0000, v181
	v_lshlrev_b32_e32 v220, 16, v185
	v_and_b32_e32 v221, 0xffff0000, v185
	v_pk_add_f32 v[218:219], v[218:219], v[220:221]
	v_pk_add_f32 v[200:201], v[200:201], v[218:219]
	v_add_f32_e32 v202, v186, v187
	v_add_f32_e32 v203, v188, v189
	v_add_f32_e32 v204, v190, v191
	v_add_f32_e32 v205, v192, v193
	v_add_f32_e32 v206, v194, v195
	v_add_f32_e32 v207, v196, v197
	v_add_f32_e32 v208, v198, v199
	v_add_f32_e32 v209, v200, v201
	v_xor_b32_e32 v229, 4, v228
	ds_bpermute_b32 v210, v229, v202
	ds_bpermute_b32 v211, v229, v203
	ds_bpermute_b32 v212, v229, v204
	ds_bpermute_b32 v213, v229, v205
	ds_bpermute_b32 v214, v229, v206
	ds_bpermute_b32 v215, v229, v207
	ds_bpermute_b32 v216, v229, v208
	ds_bpermute_b32 v217, v229, v209
	s_waitcnt lgkmcnt(0)
	v_add_f32_e32 v202, v202, v210
	v_add_f32_e32 v203, v203, v211
	v_add_f32_e32 v204, v204, v212
	v_add_f32_e32 v205, v205, v213
	v_add_f32_e32 v206, v206, v214
	v_add_f32_e32 v207, v207, v215
	v_add_f32_e32 v208, v208, v216
	v_add_f32_e32 v209, v209, v217
	v_xor_b32_e32 v229, 8, v228
	ds_bpermute_b32 v210, v229, v202
	ds_bpermute_b32 v211, v229, v203
	ds_bpermute_b32 v212, v229, v204
	ds_bpermute_b32 v213, v229, v205
	ds_bpermute_b32 v214, v229, v206
	ds_bpermute_b32 v215, v229, v207
	ds_bpermute_b32 v216, v229, v208
	ds_bpermute_b32 v217, v229, v209
	s_waitcnt lgkmcnt(0)
	v_add_f32_e32 v202, v202, v210
	v_add_f32_e32 v203, v203, v211
	v_add_f32_e32 v204, v204, v212
	v_add_f32_e32 v205, v205, v213
	v_add_f32_e32 v206, v206, v214
	v_add_f32_e32 v207, v207, v215
	v_add_f32_e32 v208, v208, v216
	v_add_f32_e32 v209, v209, v217
	v_xor_b32_e32 v229, 16, v228
	ds_bpermute_b32 v210, v229, v202
	ds_bpermute_b32 v211, v229, v203
	ds_bpermute_b32 v212, v229, v204
	ds_bpermute_b32 v213, v229, v205
	ds_bpermute_b32 v214, v229, v206
	ds_bpermute_b32 v215, v229, v207
	ds_bpermute_b32 v216, v229, v208
	ds_bpermute_b32 v217, v229, v209
	s_waitcnt lgkmcnt(0)
	v_add_f32_e32 v202, v202, v210
	v_add_f32_e32 v203, v203, v211
	v_add_f32_e32 v204, v204, v212
	v_add_f32_e32 v205, v205, v213
	v_add_f32_e32 v206, v206, v214
	v_add_f32_e32 v207, v207, v215
	v_add_f32_e32 v208, v208, v216
	v_add_f32_e32 v209, v209, v217
	v_xor_b32_e32 v229, 32, v228
	ds_bpermute_b32 v210, v229, v202
	ds_bpermute_b32 v211, v229, v203
	ds_bpermute_b32 v212, v229, v204
	ds_bpermute_b32 v213, v229, v205
	ds_bpermute_b32 v214, v229, v206
	ds_bpermute_b32 v215, v229, v207
	ds_bpermute_b32 v216, v229, v208
	ds_bpermute_b32 v217, v229, v209
	s_waitcnt lgkmcnt(0)
	v_add_f32_e32 v202, v202, v210
	v_add_f32_e32 v203, v203, v211
	v_add_f32_e32 v204, v204, v212
	v_add_f32_e32 v205, v205, v213
	v_add_f32_e32 v206, v206, v214
	v_add_f32_e32 v207, v207, v215
	v_add_f32_e32 v208, v208, v216
	v_add_f32_e32 v209, v209, v217
	v_xor_b32_e32 v229, 64, v228
	ds_bpermute_b32 v210, v229, v202
	ds_bpermute_b32 v211, v229, v203
	ds_bpermute_b32 v212, v229, v204
	ds_bpermute_b32 v213, v229, v205
	ds_bpermute_b32 v214, v229, v206
	ds_bpermute_b32 v215, v229, v207
	ds_bpermute_b32 v216, v229, v208
	ds_bpermute_b32 v217, v229, v209
	s_waitcnt lgkmcnt(0)
	v_add_f32_e32 v202, v202, v210
	v_add_f32_e32 v203, v203, v211
	v_add_f32_e32 v204, v204, v212
	v_add_f32_e32 v205, v205, v213
	v_add_f32_e32 v206, v206, v214
	v_add_f32_e32 v207, v207, v215
	v_add_f32_e32 v208, v208, v216
	v_add_f32_e32 v209, v209, v217
	v_xor_b32_e32 v229, 128, v228
	ds_bpermute_b32 v210, v229, v202
	ds_bpermute_b32 v211, v229, v203
	ds_bpermute_b32 v212, v229, v204
	ds_bpermute_b32 v213, v229, v205
	ds_bpermute_b32 v214, v229, v206
	ds_bpermute_b32 v215, v229, v207
	ds_bpermute_b32 v216, v229, v208
	ds_bpermute_b32 v217, v229, v209
	s_waitcnt lgkmcnt(0)
	v_add_f32_e32 v202, v202, v210
	v_add_f32_e32 v203, v203, v211
	v_add_f32_e32 v204, v204, v212
	v_add_f32_e32 v205, v205, v213
	v_add_f32_e32 v206, v206, v214
	v_add_f32_e32 v207, v207, v215
	v_add_f32_e32 v208, v208, v216
	v_add_f32_e32 v209, v209, v217
	v_mov_b32_e32 v224, 0x3a800000
	v_mul_f32_e32 v202, v202, v224
	v_mul_f32_e32 v203, v203, v224
	v_mul_f32_e32 v204, v204, v224
	v_mul_f32_e32 v205, v205, v224
	v_mul_f32_e32 v206, v206, v224
	v_mul_f32_e32 v207, v207, v224
	v_mul_f32_e32 v208, v208, v224
	v_mul_f32_e32 v209, v209, v224
	v_mov_b32_e32 v186, 0
	v_mov_b32_e32 v187, 0
	v_lshlrev_b32_e32 v218, 16, v84
	v_and_b32_e32 v219, 0xffff0000, v84
	v_lshlrev_b32_e32 v220, 16, v88
	v_and_b32_e32 v221, 0xffff0000, v88
	v_pk_add_f32 v[218:219], v[218:219], v[202:203] op_sel_hi:[1,0] neg_lo:[0,1] neg_hi:[0,1]
	v_pk_add_f32 v[220:221], v[220:221], v[202:203] op_sel_hi:[1,0] neg_lo:[0,1] neg_hi:[0,1]
	v_pk_mul_f32 v[220:221], v[220:221], v[220:221]
	v_pk_fma_f32 v[220:221], v[218:219], v[218:219], v[220:221]
	v_pk_add_f32 v[186:187], v[186:187], v[220:221]
	v_lshlrev_b32_e32 v218, 16, v85
	v_and_b32_e32 v219, 0xffff0000, v85
	v_lshlrev_b32_e32 v220, 16, v89
	v_and_b32_e32 v221, 0xffff0000, v89
	v_pk_add_f32 v[218:219], v[218:219], v[202:203] op_sel_hi:[1,0] neg_lo:[0,1] neg_hi:[0,1]
	v_pk_add_f32 v[220:221], v[220:221], v[202:203] op_sel_hi:[1,0] neg_lo:[0,1] neg_hi:[0,1]
	v_pk_mul_f32 v[220:221], v[220:221], v[220:221]
	v_pk_fma_f32 v[220:221], v[218:219], v[218:219], v[220:221]
	v_pk_add_f32 v[186:187], v[186:187], v[220:221]
	v_lshlrev_b32_e32 v218, 16, v86
	v_and_b32_e32 v219, 0xffff0000, v86
	v_lshlrev_b32_e32 v220, 16, v90
	v_and_b32_e32 v221, 0xffff0000, v90
	v_pk_add_f32 v[218:219], v[218:219], v[202:203] op_sel_hi:[1,0] neg_lo:[0,1] neg_hi:[0,1]
	v_pk_add_f32 v[220:221], v[220:221], v[202:203] op_sel_hi:[1,0] neg_lo:[0,1] neg_hi:[0,1]
	v_pk_mul_f32 v[220:221], v[220:221], v[220:221]
	v_pk_fma_f32 v[220:221], v[218:219], v[218:219], v[220:221]
	v_pk_add_f32 v[186:187], v[186:187], v[220:221]
	v_lshlrev_b32_e32 v218, 16, v87
	v_and_b32_e32 v219, 0xffff0000, v87
	v_lshlrev_b32_e32 v220, 16, v91
	v_and_b32_e32 v221, 0xffff0000, v91
	v_pk_add_f32 v[218:219], v[218:219], v[202:203] op_sel_hi:[1,0] neg_lo:[0,1] neg_hi:[0,1]
	v_pk_add_f32 v[220:221], v[220:221], v[202:203] op_sel_hi:[1,0] neg_lo:[0,1] neg_hi:[0,1]
	v_pk_mul_f32 v[220:221], v[220:221], v[220:221]
	v_pk_fma_f32 v[220:221], v[218:219], v[218:219], v[220:221]
	v_pk_add_f32 v[186:187], v[186:187], v[220:221]
	v_mov_b32_e32 v188, 0
	v_mov_b32_e32 v189, 0
	v_lshlrev_b32_e32 v218, 16, v92
	v_and_b32_e32 v219, 0xffff0000, v92
	v_lshlrev_b32_e32 v220, 16, v110
	v_and_b32_e32 v221, 0xffff0000, v110
	v_pk_add_f32 v[218:219], v[218:219], v[202:203] op_sel:[0,1] neg_lo:[0,1] neg_hi:[0,1]
	v_pk_add_f32 v[220:221], v[220:221], v[202:203] op_sel:[0,1] neg_lo:[0,1] neg_hi:[0,1]
	v_pk_mul_f32 v[220:221], v[220:221], v[220:221]
	v_pk_fma_f32 v[220:221], v[218:219], v[218:219], v[220:221]
	v_pk_add_f32 v[188:189], v[188:189], v[220:221]
	v_lshlrev_b32_e32 v218, 16, v93
	v_and_b32_e32 v219, 0xffff0000, v93
	v_lshlrev_b32_e32 v220, 16, v111
	v_and_b32_e32 v221, 0xffff0000, v111
	v_pk_add_f32 v[218:219], v[218:219], v[202:203] op_sel:[0,1] neg_lo:[0,1] neg_hi:[0,1]
	v_pk_add_f32 v[220:221], v[220:221], v[202:203] op_sel:[0,1] neg_lo:[0,1] neg_hi:[0,1]
	v_pk_mul_f32 v[220:221], v[220:221], v[220:221]
	v_pk_fma_f32 v[220:221], v[218:219], v[218:219], v[220:221]
	v_pk_add_f32 v[188:189], v[188:189], v[220:221]
	v_lshlrev_b32_e32 v218, 16, v94
	v_and_b32_e32 v219, 0xffff0000, v94
	v_lshlrev_b32_e32 v220, 16, v112
	v_and_b32_e32 v221, 0xffff0000, v112
	v_pk_add_f32 v[218:219], v[218:219], v[202:203] op_sel:[0,1] neg_lo:[0,1] neg_hi:[0,1]
	v_pk_add_f32 v[220:221], v[220:221], v[202:203] op_sel:[0,1] neg_lo:[0,1] neg_hi:[0,1]
	v_pk_mul_f32 v[220:221], v[220:221], v[220:221]
	v_pk_fma_f32 v[220:221], v[218:219], v[218:219], v[220:221]
	v_pk_add_f32 v[188:189], v[188:189], v[220:221]
	v_lshlrev_b32_e32 v218, 16, v95
	v_and_b32_e32 v219, 0xffff0000, v95
	v_lshlrev_b32_e32 v220, 16, v113
	v_and_b32_e32 v221, 0xffff0000, v113
	v_pk_add_f32 v[218:219], v[218:219], v[202:203] op_sel:[0,1] neg_lo:[0,1] neg_hi:[0,1]
	v_pk_add_f32 v[220:221], v[220:221], v[202:203] op_sel:[0,1] neg_lo:[0,1] neg_hi:[0,1]
	v_pk_mul_f32 v[220:221], v[220:221], v[220:221]
	v_pk_fma_f32 v[220:221], v[218:219], v[218:219], v[220:221]
	v_pk_add_f32 v[188:189], v[188:189], v[220:221]
	v_mov_b32_e32 v190, 0
	v_mov_b32_e32 v191, 0
	v_lshlrev_b32_e32 v218, 16, v114
	v_and_b32_e32 v219, 0xffff0000, v114
	v_lshlrev_b32_e32 v220, 16, v118
	v_and_b32_e32 v221, 0xffff0000, v118
	v_pk_add_f32 v[218:219], v[218:219], v[204:205] op_sel_hi:[1,0] neg_lo:[0,1] neg_hi:[0,1]
	v_pk_add_f32 v[220:221], v[220:221], v[204:205] op_sel_hi:[1,0] neg_lo:[0,1] neg_hi:[0,1]
	v_pk_mul_f32 v[220:221], v[220:221], v[220:221]
	v_pk_fma_f32 v[220:221], v[218:219], v[218:219], v[220:221]
	v_pk_add_f32 v[190:191], v[190:191], v[220:221]
	v_lshlrev_b32_e32 v218, 16, v115
	v_and_b32_e32 v219, 0xffff0000, v115
	v_lshlrev_b32_e32 v220, 16, v119
	v_and_b32_e32 v221, 0xffff0000, v119
	v_pk_add_f32 v[218:219], v[218:219], v[204:205] op_sel_hi:[1,0] neg_lo:[0,1] neg_hi:[0,1]
	v_pk_add_f32 v[220:221], v[220:221], v[204:205] op_sel_hi:[1,0] neg_lo:[0,1] neg_hi:[0,1]
	v_pk_mul_f32 v[220:221], v[220:221], v[220:221]
	v_pk_fma_f32 v[220:221], v[218:219], v[218:219], v[220:221]
	v_pk_add_f32 v[190:191], v[190:191], v[220:221]
	v_lshlrev_b32_e32 v218, 16, v116
	v_and_b32_e32 v219, 0xffff0000, v116
	v_lshlrev_b32_e32 v220, 16, v120
	v_and_b32_e32 v221, 0xffff0000, v120
	v_pk_add_f32 v[218:219], v[218:219], v[204:205] op_sel_hi:[1,0] neg_lo:[0,1] neg_hi:[0,1]
	v_pk_add_f32 v[220:221], v[220:221], v[204:205] op_sel_hi:[1,0] neg_lo:[0,1] neg_hi:[0,1]
	v_pk_mul_f32 v[220:221], v[220:221], v[220:221]
	v_pk_fma_f32 v[220:221], v[218:219], v[218:219], v[220:221]
	v_pk_add_f32 v[190:191], v[190:191], v[220:221]
	v_lshlrev_b32_e32 v218, 16, v117
	v_and_b32_e32 v219, 0xffff0000, v117
	v_lshlrev_b32_e32 v220, 16, v121
	v_and_b32_e32 v221, 0xffff0000, v121
	v_pk_add_f32 v[218:219], v[218:219], v[204:205] op_sel_hi:[1,0] neg_lo:[0,1] neg_hi:[0,1]
	v_pk_add_f32 v[220:221], v[220:221], v[204:205] op_sel_hi:[1,0] neg_lo:[0,1] neg_hi:[0,1]
	v_pk_mul_f32 v[220:221], v[220:221], v[220:221]
	v_pk_fma_f32 v[220:221], v[218:219], v[218:219], v[220:221]
	v_pk_add_f32 v[190:191], v[190:191], v[220:221]
	v_mov_b32_e32 v192, 0
	v_mov_b32_e32 v193, 0
	v_lshlrev_b32_e32 v218, 16, v122
	v_and_b32_e32 v219, 0xffff0000, v122
	v_lshlrev_b32_e32 v220, 16, v148
	v_and_b32_e32 v221, 0xffff0000, v148
	v_pk_add_f32 v[218:219], v[218:219], v[204:205] op_sel:[0,1] neg_lo:[0,1] neg_hi:[0,1]
	v_pk_add_f32 v[220:221], v[220:221], v[204:205] op_sel:[0,1] neg_lo:[0,1] neg_hi:[0,1]
	v_pk_mul_f32 v[220:221], v[220:221], v[220:221]
	v_pk_fma_f32 v[220:221], v[218:219], v[218:219], v[220:221]
	v_pk_add_f32 v[192:193], v[192:193], v[220:221]
	v_lshlrev_b32_e32 v218, 16, v123
	v_and_b32_e32 v219, 0xffff0000, v123
	v_lshlrev_b32_e32 v220, 16, v149
	v_and_b32_e32 v221, 0xffff0000, v149
	v_pk_add_f32 v[218:219], v[218:219], v[204:205] op_sel:[0,1] neg_lo:[0,1] neg_hi:[0,1]
	v_pk_add_f32 v[220:221], v[220:221], v[204:205] op_sel:[0,1] neg_lo:[0,1] neg_hi:[0,1]
	v_pk_mul_f32 v[220:221], v[220:221], v[220:221]
	v_pk_fma_f32 v[220:221], v[218:219], v[218:219], v[220:221]
	v_pk_add_f32 v[192:193], v[192:193], v[220:221]
	v_lshlrev_b32_e32 v218, 16, v124
	v_and_b32_e32 v219, 0xffff0000, v124
	v_lshlrev_b32_e32 v220, 16, v150
	v_and_b32_e32 v221, 0xffff0000, v150
	v_pk_add_f32 v[218:219], v[218:219], v[204:205] op_sel:[0,1] neg_lo:[0,1] neg_hi:[0,1]
	v_pk_add_f32 v[220:221], v[220:221], v[204:205] op_sel:[0,1] neg_lo:[0,1] neg_hi:[0,1]
	v_pk_mul_f32 v[220:221], v[220:221], v[220:221]
	v_pk_fma_f32 v[220:221], v[218:219], v[218:219], v[220:221]
	v_pk_add_f32 v[192:193], v[192:193], v[220:221]
	v_lshlrev_b32_e32 v218, 16, v125
	v_and_b32_e32 v219, 0xffff0000, v125
	v_lshlrev_b32_e32 v220, 16, v151
	v_and_b32_e32 v221, 0xffff0000, v151
	v_pk_add_f32 v[218:219], v[218:219], v[204:205] op_sel:[0,1] neg_lo:[0,1] neg_hi:[0,1]
	v_pk_add_f32 v[220:221], v[220:221], v[204:205] op_sel:[0,1] neg_lo:[0,1] neg_hi:[0,1]
	v_pk_mul_f32 v[220:221], v[220:221], v[220:221]
	v_pk_fma_f32 v[220:221], v[218:219], v[218:219], v[220:221]
	v_pk_add_f32 v[192:193], v[192:193], v[220:221]
	v_mov_b32_e32 v194, 0
	v_mov_b32_e32 v195, 0
	v_lshlrev_b32_e32 v218, 16, v152
	v_and_b32_e32 v219, 0xffff0000, v152
	v_lshlrev_b32_e32 v220, 16, v156
	v_and_b32_e32 v221, 0xffff0000, v156
	v_pk_add_f32 v[218:219], v[218:219], v[206:207] op_sel_hi:[1,0] neg_lo:[0,1] neg_hi:[0,1]
	v_pk_add_f32 v[220:221], v[220:221], v[206:207] op_sel_hi:[1,0] neg_lo:[0,1] neg_hi:[0,1]
	v_pk_mul_f32 v[220:221], v[220:221], v[220:221]
	v_pk_fma_f32 v[220:221], v[218:219], v[218:219], v[220:221]
	v_pk_add_f32 v[194:195], v[194:195], v[220:221]
	v_lshlrev_b32_e32 v218, 16, v153
	v_and_b32_e32 v219, 0xffff0000, v153
	v_lshlrev_b32_e32 v220, 16, v157
	v_and_b32_e32 v221, 0xffff0000, v157
	v_pk_add_f32 v[218:219], v[218:219], v[206:207] op_sel_hi:[1,0] neg_lo:[0,1] neg_hi:[0,1]
	v_pk_add_f32 v[220:221], v[220:221], v[206:207] op_sel_hi:[1,0] neg_lo:[0,1] neg_hi:[0,1]
	v_pk_mul_f32 v[220:221], v[220:221], v[220:221]
	v_pk_fma_f32 v[220:221], v[218:219], v[218:219], v[220:221]
	v_pk_add_f32 v[194:195], v[194:195], v[220:221]
	v_lshlrev_b32_e32 v218, 16, v154
	v_and_b32_e32 v219, 0xffff0000, v154
	v_lshlrev_b32_e32 v220, 16, v158
	v_and_b32_e32 v221, 0xffff0000, v158
	v_pk_add_f32 v[218:219], v[218:219], v[206:207] op_sel_hi:[1,0] neg_lo:[0,1] neg_hi:[0,1]
	v_pk_add_f32 v[220:221], v[220:221], v[206:207] op_sel_hi:[1,0] neg_lo:[0,1] neg_hi:[0,1]
	v_pk_mul_f32 v[220:221], v[220:221], v[220:221]
	v_pk_fma_f32 v[220:221], v[218:219], v[218:219], v[220:221]
	v_pk_add_f32 v[194:195], v[194:195], v[220:221]
	v_lshlrev_b32_e32 v218, 16, v155
	v_and_b32_e32 v219, 0xffff0000, v155
	v_lshlrev_b32_e32 v220, 16, v159
	v_and_b32_e32 v221, 0xffff0000, v159
	v_pk_add_f32 v[218:219], v[218:219], v[206:207] op_sel_hi:[1,0] neg_lo:[0,1] neg_hi:[0,1]
	v_pk_add_f32 v[220:221], v[220:221], v[206:207] op_sel_hi:[1,0] neg_lo:[0,1] neg_hi:[0,1]
	v_pk_mul_f32 v[220:221], v[220:221], v[220:221]
	v_pk_fma_f32 v[220:221], v[218:219], v[218:219], v[220:221]
	v_pk_add_f32 v[194:195], v[194:195], v[220:221]
	v_mov_b32_e32 v196, 0
	v_mov_b32_e32 v197, 0
	v_lshlrev_b32_e32 v218, 16, v160
	v_and_b32_e32 v219, 0xffff0000, v160
	v_lshlrev_b32_e32 v220, 16, v166
	v_and_b32_e32 v221, 0xffff0000, v166
	v_pk_add_f32 v[218:219], v[218:219], v[206:207] op_sel:[0,1] neg_lo:[0,1] neg_hi:[0,1]
	v_pk_add_f32 v[220:221], v[220:221], v[206:207] op_sel:[0,1] neg_lo:[0,1] neg_hi:[0,1]
	v_pk_mul_f32 v[220:221], v[220:221], v[220:221]
	v_pk_fma_f32 v[220:221], v[218:219], v[218:219], v[220:221]
	v_pk_add_f32 v[196:197], v[196:197], v[220:221]
	v_lshlrev_b32_e32 v218, 16, v161
	v_and_b32_e32 v219, 0xffff0000, v161
	v_lshlrev_b32_e32 v220, 16, v167
	v_and_b32_e32 v221, 0xffff0000, v167
	v_pk_add_f32 v[218:219], v[218:219], v[206:207] op_sel:[0,1] neg_lo:[0,1] neg_hi:[0,1]
	v_pk_add_f32 v[220:221], v[220:221], v[206:207] op_sel:[0,1] neg_lo:[0,1] neg_hi:[0,1]
	v_pk_mul_f32 v[220:221], v[220:221], v[220:221]
	v_pk_fma_f32 v[220:221], v[218:219], v[218:219], v[220:221]
	v_pk_add_f32 v[196:197], v[196:197], v[220:221]
	v_lshlrev_b32_e32 v218, 16, v162
	v_and_b32_e32 v219, 0xffff0000, v162
	v_lshlrev_b32_e32 v220, 16, v168
	v_and_b32_e32 v221, 0xffff0000, v168
	v_pk_add_f32 v[218:219], v[218:219], v[206:207] op_sel:[0,1] neg_lo:[0,1] neg_hi:[0,1]
	v_pk_add_f32 v[220:221], v[220:221], v[206:207] op_sel:[0,1] neg_lo:[0,1] neg_hi:[0,1]
	v_pk_mul_f32 v[220:221], v[220:221], v[220:221]
	v_pk_fma_f32 v[220:221], v[218:219], v[218:219], v[220:221]
	v_pk_add_f32 v[196:197], v[196:197], v[220:221]
	v_lshlrev_b32_e32 v218, 16, v163
	v_and_b32_e32 v219, 0xffff0000, v163
	v_lshlrev_b32_e32 v220, 16, v169
	v_and_b32_e32 v221, 0xffff0000, v169
	v_pk_add_f32 v[218:219], v[218:219], v[206:207] op_sel:[0,1] neg_lo:[0,1] neg_hi:[0,1]
	v_pk_add_f32 v[220:221], v[220:221], v[206:207] op_sel:[0,1] neg_lo:[0,1] neg_hi:[0,1]
	v_pk_mul_f32 v[220:221], v[220:221], v[220:221]
	v_pk_fma_f32 v[220:221], v[218:219], v[218:219], v[220:221]
	v_pk_add_f32 v[196:197], v[196:197], v[220:221]
	v_mov_b32_e32 v198, 0
	v_mov_b32_e32 v199, 0
	v_lshlrev_b32_e32 v218, 16, v170
	v_and_b32_e32 v219, 0xffff0000, v170
	v_lshlrev_b32_e32 v220, 16, v174
	v_and_b32_e32 v221, 0xffff0000, v174
	v_pk_add_f32 v[218:219], v[218:219], v[208:209] op_sel_hi:[1,0] neg_lo:[0,1] neg_hi:[0,1]
	v_pk_add_f32 v[220:221], v[220:221], v[208:209] op_sel_hi:[1,0] neg_lo:[0,1] neg_hi:[0,1]
	v_pk_mul_f32 v[220:221], v[220:221], v[220:221]
	v_pk_fma_f32 v[220:221], v[218:219], v[218:219], v[220:221]
	v_pk_add_f32 v[198:199], v[198:199], v[220:221]
	v_lshlrev_b32_e32 v218, 16, v171
	v_and_b32_e32 v219, 0xffff0000, v171
	v_lshlrev_b32_e32 v220, 16, v175
	v_and_b32_e32 v221, 0xffff0000, v175
	v_pk_add_f32 v[218:219], v[218:219], v[208:209] op_sel_hi:[1,0] neg_lo:[0,1] neg_hi:[0,1]
	v_pk_add_f32 v[220:221], v[220:221], v[208:209] op_sel_hi:[1,0] neg_lo:[0,1] neg_hi:[0,1]
	v_pk_mul_f32 v[220:221], v[220:221], v[220:221]
	v_pk_fma_f32 v[220:221], v[218:219], v[218:219], v[220:221]
	v_pk_add_f32 v[198:199], v[198:199], v[220:221]
	v_lshlrev_b32_e32 v218, 16, v172
	v_and_b32_e32 v219, 0xffff0000, v172
	v_lshlrev_b32_e32 v220, 16, v176
	v_and_b32_e32 v221, 0xffff0000, v176
	v_pk_add_f32 v[218:219], v[218:219], v[208:209] op_sel_hi:[1,0] neg_lo:[0,1] neg_hi:[0,1]
	v_pk_add_f32 v[220:221], v[220:221], v[208:209] op_sel_hi:[1,0] neg_lo:[0,1] neg_hi:[0,1]
	v_pk_mul_f32 v[220:221], v[220:221], v[220:221]
	v_pk_fma_f32 v[220:221], v[218:219], v[218:219], v[220:221]
	v_pk_add_f32 v[198:199], v[198:199], v[220:221]
	v_lshlrev_b32_e32 v218, 16, v173
	v_and_b32_e32 v219, 0xffff0000, v173
	v_lshlrev_b32_e32 v220, 16, v177
	v_and_b32_e32 v221, 0xffff0000, v177
	v_pk_add_f32 v[218:219], v[218:219], v[208:209] op_sel_hi:[1,0] neg_lo:[0,1] neg_hi:[0,1]
	v_pk_add_f32 v[220:221], v[220:221], v[208:209] op_sel_hi:[1,0] neg_lo:[0,1] neg_hi:[0,1]
	v_pk_mul_f32 v[220:221], v[220:221], v[220:221]
	v_pk_fma_f32 v[220:221], v[218:219], v[218:219], v[220:221]
	v_pk_add_f32 v[198:199], v[198:199], v[220:221]
	v_mov_b32_e32 v200, 0
	v_mov_b32_e32 v201, 0
	v_lshlrev_b32_e32 v218, 16, v178
	v_and_b32_e32 v219, 0xffff0000, v178
	v_lshlrev_b32_e32 v220, 16, v182
	v_and_b32_e32 v221, 0xffff0000, v182
	v_pk_add_f32 v[218:219], v[218:219], v[208:209] op_sel:[0,1] neg_lo:[0,1] neg_hi:[0,1]
	v_pk_add_f32 v[220:221], v[220:221], v[208:209] op_sel:[0,1] neg_lo:[0,1] neg_hi:[0,1]
	v_pk_mul_f32 v[220:221], v[220:221], v[220:221]
	v_pk_fma_f32 v[220:221], v[218:219], v[218:219], v[220:221]
	v_pk_add_f32 v[200:201], v[200:201], v[220:221]
	v_lshlrev_b32_e32 v218, 16, v179
	v_and_b32_e32 v219, 0xffff0000, v179
	v_lshlrev_b32_e32 v220, 16, v183
	v_and_b32_e32 v221, 0xffff0000, v183
	v_pk_add_f32 v[218:219], v[218:219], v[208:209] op_sel:[0,1] neg_lo:[0,1] neg_hi:[0,1]
	v_pk_add_f32 v[220:221], v[220:221], v[208:209] op_sel:[0,1] neg_lo:[0,1] neg_hi:[0,1]
	v_pk_mul_f32 v[220:221], v[220:221], v[220:221]
	v_pk_fma_f32 v[220:221], v[218:219], v[218:219], v[220:221]
	v_pk_add_f32 v[200:201], v[200:201], v[220:221]
	v_lshlrev_b32_e32 v218, 16, v180
	v_and_b32_e32 v219, 0xffff0000, v180
	v_lshlrev_b32_e32 v220, 16, v184
	v_and_b32_e32 v221, 0xffff0000, v184
	v_pk_add_f32 v[218:219], v[218:219], v[208:209] op_sel:[0,1] neg_lo:[0,1] neg_hi:[0,1]
	v_pk_add_f32 v[220:221], v[220:221], v[208:209] op_sel:[0,1] neg_lo:[0,1] neg_hi:[0,1]
	v_pk_mul_f32 v[220:221], v[220:221], v[220:221]
	v_pk_fma_f32 v[220:221], v[218:219], v[218:219], v[220:221]
	v_pk_add_f32 v[200:201], v[200:201], v[220:221]
	v_lshlrev_b32_e32 v218, 16, v181
	v_and_b32_e32 v219, 0xffff0000, v181
	v_lshlrev_b32_e32 v220, 16, v185
	v_and_b32_e32 v221, 0xffff0000, v185
	v_pk_add_f32 v[218:219], v[218:219], v[208:209] op_sel:[0,1] neg_lo:[0,1] neg_hi:[0,1]
	v_pk_add_f32 v[220:221], v[220:221], v[208:209] op_sel:[0,1] neg_lo:[0,1] neg_hi:[0,1]
	v_pk_mul_f32 v[220:221], v[220:221], v[220:221]
	v_pk_fma_f32 v[220:221], v[218:219], v[218:219], v[220:221]
	v_pk_add_f32 v[200:201], v[200:201], v[220:221]
	v_add_f32_e32 v210, v186, v187
	v_add_f32_e32 v211, v188, v189
	v_add_f32_e32 v212, v190, v191
	v_add_f32_e32 v213, v192, v193
	v_add_f32_e32 v214, v194, v195
	v_add_f32_e32 v215, v196, v197
	v_add_f32_e32 v216, v198, v199
	v_add_f32_e32 v217, v200, v201
	v_xor_b32_e32 v229, 4, v228
	ds_bpermute_b32 v186, v229, v210
	ds_bpermute_b32 v187, v229, v211
	ds_bpermute_b32 v188, v229, v212
	ds_bpermute_b32 v189, v229, v213
	ds_bpermute_b32 v190, v229, v214
	ds_bpermute_b32 v191, v229, v215
	ds_bpermute_b32 v192, v229, v216
	ds_bpermute_b32 v193, v229, v217
	s_waitcnt lgkmcnt(0)
	v_add_f32_e32 v210, v210, v186
	v_add_f32_e32 v211, v211, v187
	v_add_f32_e32 v212, v212, v188
	v_add_f32_e32 v213, v213, v189
	v_add_f32_e32 v214, v214, v190
	v_add_f32_e32 v215, v215, v191
	v_add_f32_e32 v216, v216, v192
	v_add_f32_e32 v217, v217, v193
	v_xor_b32_e32 v229, 8, v228
	ds_bpermute_b32 v186, v229, v210
	ds_bpermute_b32 v187, v229, v211
	ds_bpermute_b32 v188, v229, v212
	ds_bpermute_b32 v189, v229, v213
	ds_bpermute_b32 v190, v229, v214
	ds_bpermute_b32 v191, v229, v215
	ds_bpermute_b32 v192, v229, v216
	ds_bpermute_b32 v193, v229, v217
	s_waitcnt lgkmcnt(0)
	v_add_f32_e32 v210, v210, v186
	v_add_f32_e32 v211, v211, v187
	v_add_f32_e32 v212, v212, v188
	v_add_f32_e32 v213, v213, v189
	v_add_f32_e32 v214, v214, v190
	v_add_f32_e32 v215, v215, v191
	v_add_f32_e32 v216, v216, v192
	v_add_f32_e32 v217, v217, v193
	v_xor_b32_e32 v229, 16, v228
	ds_bpermute_b32 v186, v229, v210
	ds_bpermute_b32 v187, v229, v211
	ds_bpermute_b32 v188, v229, v212
	ds_bpermute_b32 v189, v229, v213
	ds_bpermute_b32 v190, v229, v214
	ds_bpermute_b32 v191, v229, v215
	ds_bpermute_b32 v192, v229, v216
	ds_bpermute_b32 v193, v229, v217
	s_waitcnt lgkmcnt(0)
	v_add_f32_e32 v210, v210, v186
	v_add_f32_e32 v211, v211, v187
	v_add_f32_e32 v212, v212, v188
	v_add_f32_e32 v213, v213, v189
	v_add_f32_e32 v214, v214, v190
	v_add_f32_e32 v215, v215, v191
	v_add_f32_e32 v216, v216, v192
	v_add_f32_e32 v217, v217, v193
	v_xor_b32_e32 v229, 32, v228
	ds_bpermute_b32 v186, v229, v210
	ds_bpermute_b32 v187, v229, v211
	ds_bpermute_b32 v188, v229, v212
	ds_bpermute_b32 v189, v229, v213
	ds_bpermute_b32 v190, v229, v214
	ds_bpermute_b32 v191, v229, v215
	ds_bpermute_b32 v192, v229, v216
	ds_bpermute_b32 v193, v229, v217
	s_waitcnt lgkmcnt(0)
	v_add_f32_e32 v210, v210, v186
	v_add_f32_e32 v211, v211, v187
	v_add_f32_e32 v212, v212, v188
	v_add_f32_e32 v213, v213, v189
	v_add_f32_e32 v214, v214, v190
	v_add_f32_e32 v215, v215, v191
	v_add_f32_e32 v216, v216, v192
	v_add_f32_e32 v217, v217, v193
	v_xor_b32_e32 v229, 64, v228
	ds_bpermute_b32 v186, v229, v210
	ds_bpermute_b32 v187, v229, v211
	ds_bpermute_b32 v188, v229, v212
	ds_bpermute_b32 v189, v229, v213
	ds_bpermute_b32 v190, v229, v214
	ds_bpermute_b32 v191, v229, v215
	ds_bpermute_b32 v192, v229, v216
	ds_bpermute_b32 v193, v229, v217
	s_waitcnt lgkmcnt(0)
	v_add_f32_e32 v210, v210, v186
	v_add_f32_e32 v211, v211, v187
	v_add_f32_e32 v212, v212, v188
	v_add_f32_e32 v213, v213, v189
	v_add_f32_e32 v214, v214, v190
	v_add_f32_e32 v215, v215, v191
	v_add_f32_e32 v216, v216, v192
	v_add_f32_e32 v217, v217, v193
	v_xor_b32_e32 v229, 128, v228
	ds_bpermute_b32 v186, v229, v210
	ds_bpermute_b32 v187, v229, v211
	ds_bpermute_b32 v188, v229, v212
	ds_bpermute_b32 v189, v229, v213
	ds_bpermute_b32 v190, v229, v214
	ds_bpermute_b32 v191, v229, v215
	ds_bpermute_b32 v192, v229, v216
	ds_bpermute_b32 v193, v229, v217
	s_waitcnt lgkmcnt(0)
	v_add_f32_e32 v210, v210, v186
	v_add_f32_e32 v211, v211, v187
	v_add_f32_e32 v212, v212, v188
	v_add_f32_e32 v213, v213, v189
	v_add_f32_e32 v214, v214, v190
	v_add_f32_e32 v215, v215, v191
	v_add_f32_e32 v216, v216, v192
	v_add_f32_e32 v217, v217, v193
	v_mov_b32_e32 v225, 0x358637bd
	v_fma_f32 v210, v210, v224, v225
	v_rsq_f32_e32 v210, v210
	v_fma_f32 v211, v211, v224, v225
	v_rsq_f32_e32 v211, v211
	v_fma_f32 v212, v212, v224, v225
	v_rsq_f32_e32 v212, v212
	v_fma_f32 v213, v213, v224, v225
	v_rsq_f32_e32 v213, v213
	v_fma_f32 v214, v214, v224, v225
	v_rsq_f32_e32 v214, v214
	v_fma_f32 v215, v215, v224, v225
	v_rsq_f32_e32 v215, v215
	v_fma_f32 v216, v216, v224, v225
	v_rsq_f32_e32 v216, v216
	v_fma_f32 v217, v217, v224, v225
	v_rsq_f32_e32 v217, v217
	s_and_saveexec_b64 s[56:57], s[4:5]
	v_cndmask_b32_e64 v186, v88, v84, s[6:7]
	v_cndmask_b32_e64 v187, v89, v85, s[6:7]
	v_cndmask_b32_e64 v188, v90, v86, s[6:7]
	v_cndmask_b32_e64 v189, v91, v87, s[6:7]
	v_lshlrev_b32_e32 v222, 16, v186
	v_and_b32_e32 v223, 0xffff0000, v186
	v_pk_add_f32 v[222:223], v[222:223], v[202:203] op_sel_hi:[1,0] neg_lo:[0,1] neg_hi:[0,1]
	v_pk_mul_f32 v[222:223], v[222:223], v[210:211] op_sel_hi:[1,0]
	v_pk_fma_f32 v[222:223], v[222:223], v[0:1], v[8:9]
	v_cvt_pk_bf16_f32 v232, v222, v223
	v_lshlrev_b32_e32 v222, 16, v187
	v_and_b32_e32 v223, 0xffff0000, v187
	v_pk_add_f32 v[222:223], v[222:223], v[202:203] op_sel_hi:[1,0] neg_lo:[0,1] neg_hi:[0,1]
	v_pk_mul_f32 v[222:223], v[222:223], v[210:211] op_sel_hi:[1,0]
	v_pk_fma_f32 v[222:223], v[222:223], v[2:3], v[10:11]
	v_cvt_pk_bf16_f32 v233, v222, v223
	v_lshlrev_b32_e32 v222, 16, v188
	v_and_b32_e32 v223, 0xffff0000, v188
	v_pk_add_f32 v[222:223], v[222:223], v[202:203] op_sel_hi:[1,0] neg_lo:[0,1] neg_hi:[0,1]
	v_pk_mul_f32 v[222:223], v[222:223], v[210:211] op_sel_hi:[1,0]
	v_pk_fma_f32 v[222:223], v[222:223], v[4:5], v[12:13]
	v_cvt_pk_bf16_f32 v234, v222, v223
	v_lshlrev_b32_e32 v222, 16, v189
	v_and_b32_e32 v223, 0xffff0000, v189
	v_pk_add_f32 v[222:223], v[222:223], v[202:203] op_sel_hi:[1,0] neg_lo:[0,1] neg_hi:[0,1]
	v_pk_mul_f32 v[222:223], v[222:223], v[210:211] op_sel_hi:[1,0]
	v_pk_fma_f32 v[222:223], v[222:223], v[6:7], v[14:15]
	v_cvt_pk_bf16_f32 v235, v222, v223
	ds_write_b128 v107, v[232:235] offset:4224
	v_cndmask_b32_e64 v186, v110, v92, s[6:7]
	v_cndmask_b32_e64 v187, v111, v93, s[6:7]
	v_cndmask_b32_e64 v188, v112, v94, s[6:7]
	v_cndmask_b32_e64 v189, v113, v95, s[6:7]
	v_lshlrev_b32_e32 v222, 16, v186
	v_and_b32_e32 v223, 0xffff0000, v186
	v_pk_add_f32 v[222:223], v[222:223], v[202:203] op_sel:[0,1] neg_lo:[0,1] neg_hi:[0,1]
	v_pk_mul_f32 v[222:223], v[222:223], v[210:211] op_sel:[0,1]
	v_pk_fma_f32 v[222:223], v[222:223], v[0:1], v[8:9]
	v_cvt_pk_bf16_f32 v236, v222, v223
	v_lshlrev_b32_e32 v222, 16, v187
	v_and_b32_e32 v223, 0xffff0000, v187
	v_pk_add_f32 v[222:223], v[222:223], v[202:203] op_sel:[0,1] neg_lo:[0,1] neg_hi:[0,1]
	v_pk_mul_f32 v[222:223], v[222:223], v[210:211] op_sel:[0,1]
	v_pk_fma_f32 v[222:223], v[222:223], v[2:3], v[10:11]
	v_cvt_pk_bf16_f32 v237, v222, v223
	v_lshlrev_b32_e32 v222, 16, v188
	v_and_b32_e32 v223, 0xffff0000, v188
	v_pk_add_f32 v[222:223], v[222:223], v[202:203] op_sel:[0,1] neg_lo:[0,1] neg_hi:[0,1]
	v_pk_mul_f32 v[222:223], v[222:223], v[210:211] op_sel:[0,1]
	v_pk_fma_f32 v[222:223], v[222:223], v[4:5], v[12:13]
	v_cvt_pk_bf16_f32 v238, v222, v223
	v_lshlrev_b32_e32 v222, 16, v189
	v_and_b32_e32 v223, 0xffff0000, v189
	v_pk_add_f32 v[222:223], v[222:223], v[202:203] op_sel:[0,1] neg_lo:[0,1] neg_hi:[0,1]
	v_pk_mul_f32 v[222:223], v[222:223], v[210:211] op_sel:[0,1]
	v_pk_fma_f32 v[222:223], v[222:223], v[6:7], v[14:15]
	v_cvt_pk_bf16_f32 v239, v222, v223
	ds_write_b128 v107, v[236:239] offset:4752
	v_cndmask_b32_e64 v186, v118, v114, s[6:7]
	v_cndmask_b32_e64 v187, v119, v115, s[6:7]
	v_cndmask_b32_e64 v188, v120, v116, s[6:7]
	v_cndmask_b32_e64 v189, v121, v117, s[6:7]
	v_lshlrev_b32_e32 v222, 16, v186
	v_and_b32_e32 v223, 0xffff0000, v186
	v_pk_add_f32 v[222:223], v[222:223], v[204:205] op_sel_hi:[1,0] neg_lo:[0,1] neg_hi:[0,1]
	v_pk_mul_f32 v[222:223], v[222:223], v[212:213] op_sel_hi:[1,0]
	v_pk_fma_f32 v[222:223], v[222:223], v[0:1], v[8:9]
	v_cvt_pk_bf16_f32 v232, v222, v223
	v_lshlrev_b32_e32 v222, 16, v187
	v_and_b32_e32 v223, 0xffff0000, v187
	v_pk_add_f32 v[222:223], v[222:223], v[204:205] op_sel_hi:[1,0] neg_lo:[0,1] neg_hi:[0,1]
	v_pk_mul_f32 v[222:223], v[222:223], v[212:213] op_sel_hi:[1,0]
	v_pk_fma_f32 v[222:223], v[222:223], v[2:3], v[10:11]
	v_cvt_pk_bf16_f32 v233, v222, v223
	v_lshlrev_b32_e32 v222, 16, v188
	v_and_b32_e32 v223, 0xffff0000, v188
	v_pk_add_f32 v[222:223], v[222:223], v[204:205] op_sel_hi:[1,0] neg_lo:[0,1] neg_hi:[0,1]
	v_pk_mul_f32 v[222:223], v[222:223], v[212:213] op_sel_hi:[1,0]
	v_pk_fma_f32 v[222:223], v[222:223], v[4:5], v[12:13]
	v_cvt_pk_bf16_f32 v234, v222, v223
	v_lshlrev_b32_e32 v222, 16, v189
	v_and_b32_e32 v223, 0xffff0000, v189
	v_pk_add_f32 v[222:223], v[222:223], v[204:205] op_sel_hi:[1,0] neg_lo:[0,1] neg_hi:[0,1]
	v_pk_mul_f32 v[222:223], v[222:223], v[212:213] op_sel_hi:[1,0]
	v_pk_fma_f32 v[222:223], v[222:223], v[6:7], v[14:15]
	v_cvt_pk_bf16_f32 v235, v222, v223
	ds_write_b128 v107, v[232:235] offset:5280
	v_cndmask_b32_e64 v186, v148, v122, s[6:7]
	v_cndmask_b32_e64 v187, v149, v123, s[6:7]
	v_cndmask_b32_e64 v188, v150, v124, s[6:7]
	v_cndmask_b32_e64 v189, v151, v125, s[6:7]
	v_lshlrev_b32_e32 v222, 16, v186
	v_and_b32_e32 v223, 0xffff0000, v186
	v_pk_add_f32 v[222:223], v[222:223], v[204:205] op_sel:[0,1] neg_lo:[0,1] neg_hi:[0,1]
	v_pk_mul_f32 v[222:223], v[222:223], v[212:213] op_sel:[0,1]
	v_pk_fma_f32 v[222:223], v[222:223], v[0:1], v[8:9]
	v_cvt_pk_bf16_f32 v236, v222, v223
	v_lshlrev_b32_e32 v222, 16, v187
	v_and_b32_e32 v223, 0xffff0000, v187
	v_pk_add_f32 v[222:223], v[222:223], v[204:205] op_sel:[0,1] neg_lo:[0,1] neg_hi:[0,1]
	v_pk_mul_f32 v[222:223], v[222:223], v[212:213] op_sel:[0,1]
	v_pk_fma_f32 v[222:223], v[222:223], v[2:3], v[10:11]
	v_cvt_pk_bf16_f32 v237, v222, v223
	v_lshlrev_b32_e32 v222, 16, v188
	v_and_b32_e32 v223, 0xffff0000, v188
	v_pk_add_f32 v[222:223], v[222:223], v[204:205] op_sel:[0,1] neg_lo:[0,1] neg_hi:[0,1]
	v_pk_mul_f32 v[222:223], v[222:223], v[212:213] op_sel:[0,1]
	v_pk_fma_f32 v[222:223], v[222:223], v[4:5], v[12:13]
	v_cvt_pk_bf16_f32 v238, v222, v223
	v_lshlrev_b32_e32 v222, 16, v189
	v_and_b32_e32 v223, 0xffff0000, v189
	v_pk_add_f32 v[222:223], v[222:223], v[204:205] op_sel:[0,1] neg_lo:[0,1] neg_hi:[0,1]
	v_pk_mul_f32 v[222:223], v[222:223], v[212:213] op_sel:[0,1]
	v_pk_fma_f32 v[222:223], v[222:223], v[6:7], v[14:15]
	v_cvt_pk_bf16_f32 v239, v222, v223
	ds_write_b128 v107, v[236:239] offset:5808
	v_cndmask_b32_e64 v186, v156, v152, s[6:7]
	v_cndmask_b32_e64 v187, v157, v153, s[6:7]
	v_cndmask_b32_e64 v188, v158, v154, s[6:7]
	v_cndmask_b32_e64 v189, v159, v155, s[6:7]
	v_lshlrev_b32_e32 v222, 16, v186
	v_and_b32_e32 v223, 0xffff0000, v186
	v_pk_add_f32 v[222:223], v[222:223], v[206:207] op_sel_hi:[1,0] neg_lo:[0,1] neg_hi:[0,1]
	v_pk_mul_f32 v[222:223], v[222:223], v[214:215] op_sel_hi:[1,0]
	v_pk_fma_f32 v[222:223], v[222:223], v[0:1], v[8:9]
	v_cvt_pk_bf16_f32 v232, v222, v223
	v_lshlrev_b32_e32 v222, 16, v187
	v_and_b32_e32 v223, 0xffff0000, v187
	v_pk_add_f32 v[222:223], v[222:223], v[206:207] op_sel_hi:[1,0] neg_lo:[0,1] neg_hi:[0,1]
	v_pk_mul_f32 v[222:223], v[222:223], v[214:215] op_sel_hi:[1,0]
	v_pk_fma_f32 v[222:223], v[222:223], v[2:3], v[10:11]
	v_cvt_pk_bf16_f32 v233, v222, v223
	v_lshlrev_b32_e32 v222, 16, v188
	v_and_b32_e32 v223, 0xffff0000, v188
	v_pk_add_f32 v[222:223], v[222:223], v[206:207] op_sel_hi:[1,0] neg_lo:[0,1] neg_hi:[0,1]
	v_pk_mul_f32 v[222:223], v[222:223], v[214:215] op_sel_hi:[1,0]
	v_pk_fma_f32 v[222:223], v[222:223], v[4:5], v[12:13]
	v_cvt_pk_bf16_f32 v234, v222, v223
	v_lshlrev_b32_e32 v222, 16, v189
	v_and_b32_e32 v223, 0xffff0000, v189
	v_pk_add_f32 v[222:223], v[222:223], v[206:207] op_sel_hi:[1,0] neg_lo:[0,1] neg_hi:[0,1]
	v_pk_mul_f32 v[222:223], v[222:223], v[214:215] op_sel_hi:[1,0]
	v_pk_fma_f32 v[222:223], v[222:223], v[6:7], v[14:15]
	v_cvt_pk_bf16_f32 v235, v222, v223
	ds_write_b128 v107, v[232:235] offset:6336
	v_cndmask_b32_e64 v186, v166, v160, s[6:7]
	v_cndmask_b32_e64 v187, v167, v161, s[6:7]
	v_cndmask_b32_e64 v188, v168, v162, s[6:7]
	v_cndmask_b32_e64 v189, v169, v163, s[6:7]
	v_lshlrev_b32_e32 v222, 16, v186
	v_and_b32_e32 v223, 0xffff0000, v186
	v_pk_add_f32 v[222:223], v[222:223], v[206:207] op_sel:[0,1] neg_lo:[0,1] neg_hi:[0,1]
	v_pk_mul_f32 v[222:223], v[222:223], v[214:215] op_sel:[0,1]
	v_pk_fma_f32 v[222:223], v[222:223], v[0:1], v[8:9]
	v_cvt_pk_bf16_f32 v236, v222, v223
	v_lshlrev_b32_e32 v222, 16, v187
	v_and_b32_e32 v223, 0xffff0000, v187
	v_pk_add_f32 v[222:223], v[222:223], v[206:207] op_sel:[0,1] neg_lo:[0,1] neg_hi:[0,1]
	v_pk_mul_f32 v[222:223], v[222:223], v[214:215] op_sel:[0,1]
	v_pk_fma_f32 v[222:223], v[222:223], v[2:3], v[10:11]
	v_cvt_pk_bf16_f32 v237, v222, v223
	v_lshlrev_b32_e32 v222, 16, v188
	v_and_b32_e32 v223, 0xffff0000, v188
	v_pk_add_f32 v[222:223], v[222:223], v[206:207] op_sel:[0,1] neg_lo:[0,1] neg_hi:[0,1]
	v_pk_mul_f32 v[222:223], v[222:223], v[214:215] op_sel:[0,1]
	v_pk_fma_f32 v[222:223], v[222:223], v[4:5], v[12:13]
	v_cvt_pk_bf16_f32 v238, v222, v223
	v_lshlrev_b32_e32 v222, 16, v189
	v_and_b32_e32 v223, 0xffff0000, v189
	v_pk_add_f32 v[222:223], v[222:223], v[206:207] op_sel:[0,1] neg_lo:[0,1] neg_hi:[0,1]
	v_pk_mul_f32 v[222:223], v[222:223], v[214:215] op_sel:[0,1]
	v_pk_fma_f32 v[222:223], v[222:223], v[6:7], v[14:15]
	v_cvt_pk_bf16_f32 v239, v222, v223
	ds_write_b128 v107, v[236:239] offset:6864
	v_cndmask_b32_e64 v186, v174, v170, s[6:7]
	v_cndmask_b32_e64 v187, v175, v171, s[6:7]
	v_cndmask_b32_e64 v188, v176, v172, s[6:7]
	v_cndmask_b32_e64 v189, v177, v173, s[6:7]
	v_lshlrev_b32_e32 v222, 16, v186
	v_and_b32_e32 v223, 0xffff0000, v186
	v_pk_add_f32 v[222:223], v[222:223], v[208:209] op_sel_hi:[1,0] neg_lo:[0,1] neg_hi:[0,1]
	v_pk_mul_f32 v[222:223], v[222:223], v[216:217] op_sel_hi:[1,0]
	v_pk_fma_f32 v[222:223], v[222:223], v[0:1], v[8:9]
	v_cvt_pk_bf16_f32 v232, v222, v223
	v_lshlrev_b32_e32 v222, 16, v187
	v_and_b32_e32 v223, 0xffff0000, v187
	v_pk_add_f32 v[222:223], v[222:223], v[208:209] op_sel_hi:[1,0] neg_lo:[0,1] neg_hi:[0,1]
	v_pk_mul_f32 v[222:223], v[222:223], v[216:217] op_sel_hi:[1,0]
	v_pk_fma_f32 v[222:223], v[222:223], v[2:3], v[10:11]
	v_cvt_pk_bf16_f32 v233, v222, v223
	v_lshlrev_b32_e32 v222, 16, v188
	v_and_b32_e32 v223, 0xffff0000, v188
	v_pk_add_f32 v[222:223], v[222:223], v[208:209] op_sel_hi:[1,0] neg_lo:[0,1] neg_hi:[0,1]
	v_pk_mul_f32 v[222:223], v[222:223], v[216:217] op_sel_hi:[1,0]
	v_pk_fma_f32 v[222:223], v[222:223], v[4:5], v[12:13]
	v_cvt_pk_bf16_f32 v234, v222, v223
	v_lshlrev_b32_e32 v222, 16, v189
	v_and_b32_e32 v223, 0xffff0000, v189
	v_pk_add_f32 v[222:223], v[222:223], v[208:209] op_sel_hi:[1,0] neg_lo:[0,1] neg_hi:[0,1]
	v_pk_mul_f32 v[222:223], v[222:223], v[216:217] op_sel_hi:[1,0]
	v_pk_fma_f32 v[222:223], v[222:223], v[6:7], v[14:15]
	v_cvt_pk_bf16_f32 v235, v222, v223
	ds_write_b128 v107, v[232:235] offset:7392
	v_cndmask_b32_e64 v186, v182, v178, s[6:7]
	v_cndmask_b32_e64 v187, v183, v179, s[6:7]
	v_cndmask_b32_e64 v188, v184, v180, s[6:7]
	v_cndmask_b32_e64 v189, v185, v181, s[6:7]
	v_lshlrev_b32_e32 v222, 16, v186
	v_and_b32_e32 v223, 0xffff0000, v186
	v_pk_add_f32 v[222:223], v[222:223], v[208:209] op_sel:[0,1] neg_lo:[0,1] neg_hi:[0,1]
	v_pk_mul_f32 v[222:223], v[222:223], v[216:217] op_sel:[0,1]
	v_pk_fma_f32 v[222:223], v[222:223], v[0:1], v[8:9]
	v_cvt_pk_bf16_f32 v236, v222, v223
	v_lshlrev_b32_e32 v222, 16, v187
	v_and_b32_e32 v223, 0xffff0000, v187
	v_pk_add_f32 v[222:223], v[222:223], v[208:209] op_sel:[0,1] neg_lo:[0,1] neg_hi:[0,1]
	v_pk_mul_f32 v[222:223], v[222:223], v[216:217] op_sel:[0,1]
	v_pk_fma_f32 v[222:223], v[222:223], v[2:3], v[10:11]
	v_cvt_pk_bf16_f32 v237, v222, v223
	v_lshlrev_b32_e32 v222, 16, v188
	v_and_b32_e32 v223, 0xffff0000, v188
	v_pk_add_f32 v[222:223], v[222:223], v[208:209] op_sel:[0,1] neg_lo:[0,1] neg_hi:[0,1]
	v_pk_mul_f32 v[222:223], v[222:223], v[216:217] op_sel:[0,1]
	v_pk_fma_f32 v[222:223], v[222:223], v[4:5], v[12:13]
	v_cvt_pk_bf16_f32 v238, v222, v223
	v_lshlrev_b32_e32 v222, 16, v189
	v_and_b32_e32 v223, 0xffff0000, v189
	v_pk_add_f32 v[222:223], v[222:223], v[208:209] op_sel:[0,1] neg_lo:[0,1] neg_hi:[0,1]
	v_pk_mul_f32 v[222:223], v[222:223], v[216:217] op_sel:[0,1]
	v_pk_fma_f32 v[222:223], v[222:223], v[6:7], v[14:15]
	v_cvt_pk_bf16_f32 v239, v222, v223
	ds_write_b128 v107, v[236:239] offset:7920
	s_or_b64 exec, exec, s[56:57]
	s_branch .LBB0_349
	s_branch .LBB0_347
